# static priority in the GEMM main loops: hipcc's 96 per-phase s_setprio flips deleted, one s_setprio 1 for waves 4-7 at kernel start (the guide's static raise for one wave half, applied kernel-wide)
# baseline (speedup 1.0000x reference)
_Z6mk_fwd4Args:
	s_load_dwordx2 s[70:71], s[0:1], 0xe0
	s_load_dword s50, s[0:1], 0xe8
	s_mov_b64 s[76:77], s[0:1]
	s_add_u32 s6, s76, 0xe0
	v_and_b32_e32 v204, 0x3ff, v0
	s_addc_u32 s7, s77, 0
	v_cmp_gt_u32_e32 vcc, 16, v204
	s_and_saveexec_b64 s[0:1], vcc
	v_lshl_add_u32 v1, v204, 2, 0
	v_add_u32_e32 v1, 0x20140, v1
	v_mov_b32_e32 v2, 0
	ds_write_b32 v1, v2
	s_or_b64 exec, exec, s[0:1]
	s_waitcnt lgkmcnt(0)
	s_barrier
	v_readfirstlane_b32 s3, v204
	s_lshr_b32 s3, s3, 8
	s_cmp_eq_u32 s3, 1
	s_cbranch_scc0 .Lprio_static_done
	s_setprio 1
.Lprio_static_done:
	s_load_dwordx2 s[0:1], s[76:77], 0xd0
	s_getreg_b32 s3, hwreg(HW_REG_XCC_ID, 0, 4)
	v_cmp_eq_u32_e64 s[8:9], 0, v204
	s_waitcnt lgkmcnt(0)
	s_add_u32 s24, s0, 0x1000
	s_addc_u32 s25, s1, 0
	s_and_b32 s51, s3, 15
	s_mov_b64 s[4:5], exec
	v_writelane_b32 v253, s8, 0
	s_nop 1
	v_writelane_b32 v253, s9, 1
	s_and_b64 s[8:9], s[4:5], s[8:9]
	s_mov_b64 exec, s[8:9]
	s_cbranch_execz .LBB0_5
	s_mov_b64 s[8:9], exec
	v_mbcnt_lo_u32_b32 v1, s8, 0
	v_mbcnt_hi_u32_b32 v1, s9, v1
	v_cmp_eq_u32_e32 vcc, 0, v1
	s_and_b64 s[10:11], exec, vcc
	s_mov_b64 exec, s[10:11]
	s_cbranch_execz .LBB0_5
	s_lshl_b32 s3, s51, 8
	s_bcnt1_i32_b64 s8, s[8:9]
	v_mov_b32_e32 v1, s3
	v_mov_b32_e32 v2, s8
	global_atomic_add v1, v2, s[24:25] offset:1024

.LBB0_120:
	s_add_u32 s8, s50, 0xfffc0080
	s_addc_u32 s9, s51, -1
	s_add_i32 s10, 0, 0x10000
	s_cmp_eq_u32 s72, 12
	s_cselect_b32 s57, s43, s9
	s_cselect_b32 s56, s66, s8
	v_add_u32_e32 v140, s10, v143
	s_cselect_b32 s55, s41, s69
	s_cselect_b32 s54, s67, s68
	s_add_i32 s11, 0, 0x14000
	ds_read_b128 v[146:149], v140
	ds_read_b128 v[150:153], v140 offset:1024
	ds_read_b128 v[154:157], v140 offset:2048
	ds_read_b128 v[158:161], v140 offset:3072
	v_add_u32_e32 v140, s11, v143
	ds_read_b128 v[162:165], v140
	ds_read_b128 v[166:169], v140 offset:1024
	ds_read_b128 v[170:173], v140 offset:2048
	ds_read_b128 v[174:177], v140 offset:3072
	v_lshl_add_u64 v[140:141], s[100:101], 0, v[0:1]
	s_add_i32 m0, s52, 0x1c000
	s_nop 0
	global_load_lds_dwordx4 v[140:141], off
	v_lshl_add_u64 v[140:141], s[100:101], 0, v[130:131]
	s_add_i32 m0, s52, 0x1e000
	s_nop 0
	global_load_lds_dwordx4 v[140:141], off
	v_lshl_add_u64 v[140:141], s[50:51], 0, v[136:137]
	s_add_i32 m0, s53, 0xc000
	ds_read_b128 v[178:181], v145
	ds_read_b128 v[182:185], v145 offset:1024
	ds_read_b128 v[224:227], v145 offset:2048
	ds_read_b128 v[228:231], v145 offset:3072
	ds_read_b128 v[232:235], v145 offset:4096
	ds_read_b128 v[236:239], v145 offset:5120
	ds_read_b128 v[240:243], v145 offset:6144
	ds_read_b128 v[244:247], v145 offset:7168
	global_load_lds_dwordx4 v[140:141], off
	v_lshl_add_u64 v[140:141], s[50:51], 0, v[138:139]
	s_add_i32 m0, s53, 0xe000
	s_nop 0
	global_load_lds_dwordx4 v[140:141], off
	s_waitcnt vmcnt(8)
	s_waitcnt lgkmcnt(0)
	s_barrier
	s_waitcnt lgkmcnt(0)
	v_mfma_f32_16x16x32_bf16 v[126:129], v[146:149], v[178:181], v[126:129]
	v_mfma_f32_16x16x32_bf16 v[118:121], v[154:157], v[178:181], v[118:121]
	v_mfma_f32_16x16x32_bf16 v[110:113], v[146:149], v[224:227], v[110:113]
	v_mfma_f32_16x16x32_bf16 v[102:105], v[154:157], v[224:227], v[102:105]
	v_mfma_f32_16x16x32_bf16 v[94:97], v[146:149], v[232:235], v[94:97]
	v_mfma_f32_16x16x32_bf16 v[86:89], v[154:157], v[232:235], v[86:89]
	v_mfma_f32_16x16x32_bf16 v[78:81], v[146:149], v[240:243], v[78:81]
	v_mfma_f32_16x16x32_bf16 v[70:73], v[154:157], v[240:243], v[70:73]
	v_mfma_f32_16x16x32_bf16 v[126:129], v[150:153], v[182:185], v[126:129]
	v_mfma_f32_16x16x32_bf16 v[118:121], v[158:161], v[182:185], v[118:121]
	v_mfma_f32_16x16x32_bf16 v[110:113], v[150:153], v[228:231], v[110:113]
	v_mfma_f32_16x16x32_bf16 v[102:105], v[158:161], v[228:231], v[102:105]
	v_mfma_f32_16x16x32_bf16 v[94:97], v[150:153], v[236:239], v[94:97]
	v_mfma_f32_16x16x32_bf16 v[86:89], v[158:161], v[236:239], v[86:89]
	v_mfma_f32_16x16x32_bf16 v[78:81], v[150:153], v[244:247], v[78:81]
	v_mfma_f32_16x16x32_bf16 v[70:73], v[158:161], v[244:247], v[70:73]
	v_mfma_f32_16x16x32_bf16 v[122:125], v[162:165], v[178:181], v[122:125]
	v_mfma_f32_16x16x32_bf16 v[114:117], v[170:173], v[178:181], v[114:117]
	v_mfma_f32_16x16x32_bf16 v[106:109], v[162:165], v[224:227], v[106:109]
	v_mfma_f32_16x16x32_bf16 v[98:101], v[170:173], v[224:227], v[98:101]
	v_mfma_f32_16x16x32_bf16 v[90:93], v[162:165], v[232:235], v[90:93]
	v_mfma_f32_16x16x32_bf16 v[82:85], v[170:173], v[232:235], v[82:85]
	v_mfma_f32_16x16x32_bf16 v[74:77], v[162:165], v[240:243], v[74:77]
	v_mfma_f32_16x16x32_bf16 v[66:69], v[170:173], v[240:243], v[66:69]
	v_mfma_f32_16x16x32_bf16 v[122:125], v[166:169], v[182:185], v[122:125]
	v_mfma_f32_16x16x32_bf16 v[114:117], v[174:177], v[182:185], v[114:117]
	v_mfma_f32_16x16x32_bf16 v[106:109], v[166:169], v[228:231], v[106:109]
	v_mfma_f32_16x16x32_bf16 v[98:101], v[174:177], v[228:231], v[98:101]
	v_mfma_f32_16x16x32_bf16 v[90:93], v[166:169], v[236:239], v[90:93]
	v_mfma_f32_16x16x32_bf16 v[82:85], v[174:177], v[236:239], v[82:85]
	v_mfma_f32_16x16x32_bf16 v[74:77], v[166:169], v[244:247], v[74:77]
	v_mfma_f32_16x16x32_bf16 v[66:69], v[174:177], v[244:247], v[66:69]
	s_barrier
	s_add_i32 s8, s10, s52
	v_lshl_add_u64 v[140:141], s[54:55], 0, v[0:1]
	s_mov_b32 m0, s8
	ds_read_b128 v[178:181], v145 offset:16384
	ds_read_b128 v[182:185], v145 offset:17408
	ds_read_b128 v[224:227], v145 offset:18432
	ds_read_b128 v[228:231], v145 offset:19456
	ds_read_b128 v[232:235], v145 offset:20480
	ds_read_b128 v[236:239], v145 offset:21504
	ds_read_b128 v[240:243], v145 offset:22528
	ds_read_b128 v[244:247], v145 offset:23552
	global_load_lds_dwordx4 v[140:141], off
	s_add_i32 m0, s8, 0x2000
	v_lshl_add_u64 v[186:187], s[54:55], 0, v[130:131]
	global_load_lds_dwordx4 v[186:187], off
	v_lshl_add_u64 v[248:249], s[56:57], 0, v[132:133]
	v_lshl_add_u64 v[202:203], s[56:57], 0, v[134:135]
	s_mov_b32 m0, s53
	s_nop 0
	global_load_lds_dwordx4 v[202:203], off
	s_mov_b32 m0, s58
	s_nop 0
	global_load_lds_dwordx4 v[248:249], off
	s_waitcnt vmcnt(6)
	s_waitcnt lgkmcnt(0)
	s_barrier
	s_waitcnt lgkmcnt(0)
	v_mfma_f32_16x16x32_bf16 v[62:65], v[146:149], v[178:181], v[62:65]
	v_mfma_f32_16x16x32_bf16 v[54:57], v[154:157], v[178:181], v[54:57]
	v_mfma_f32_16x16x32_bf16 v[46:49], v[146:149], v[224:227], v[46:49]
	v_mfma_f32_16x16x32_bf16 v[38:41], v[154:157], v[224:227], v[38:41]
	v_mfma_f32_16x16x32_bf16 v[30:33], v[146:149], v[232:235], v[30:33]
	v_mfma_f32_16x16x32_bf16 v[22:25], v[154:157], v[232:235], v[22:25]
	v_mfma_f32_16x16x32_bf16 v[14:17], v[146:149], v[240:243], v[14:17]
	v_mfma_f32_16x16x32_bf16 v[6:9], v[154:157], v[240:243], v[6:9]
	v_mfma_f32_16x16x32_bf16 v[62:65], v[150:153], v[182:185], v[62:65]
	v_mfma_f32_16x16x32_bf16 v[54:57], v[158:161], v[182:185], v[54:57]
	v_mfma_f32_16x16x32_bf16 v[46:49], v[150:153], v[228:231], v[46:49]
	v_mfma_f32_16x16x32_bf16 v[38:41], v[158:161], v[228:231], v[38:41]
	v_mfma_f32_16x16x32_bf16 v[30:33], v[150:153], v[236:239], v[30:33]
	v_mfma_f32_16x16x32_bf16 v[22:25], v[158:161], v[236:239], v[22:25]
	v_mfma_f32_16x16x32_bf16 v[14:17], v[150:153], v[244:247], v[14:17]
	v_mfma_f32_16x16x32_bf16 v[6:9], v[158:161], v[244:247], v[6:9]
	v_mfma_f32_16x16x32_bf16 v[58:61], v[162:165], v[178:181], v[58:61]
	v_mfma_f32_16x16x32_bf16 v[50:53], v[170:173], v[178:181], v[50:53]
	v_mfma_f32_16x16x32_bf16 v[42:45], v[162:165], v[224:227], v[42:45]
	v_mfma_f32_16x16x32_bf16 v[34:37], v[170:173], v[224:227], v[34:37]
	v_mfma_f32_16x16x32_bf16 v[26:29], v[162:165], v[232:235], v[26:29]
	v_mfma_f32_16x16x32_bf16 v[18:21], v[170:173], v[232:235], v[18:21]
	v_mfma_f32_16x16x32_bf16 v[10:13], v[162:165], v[240:243], v[10:13]
	v_mfma_f32_16x16x32_bf16 v[2:5], v[170:173], v[240:243], v[2:5]
	v_mfma_f32_16x16x32_bf16 v[58:61], v[166:169], v[182:185], v[58:61]
	v_mfma_f32_16x16x32_bf16 v[50:53], v[174:177], v[182:185], v[50:53]
	v_mfma_f32_16x16x32_bf16 v[42:45], v[166:169], v[228:231], v[42:45]
	v_mfma_f32_16x16x32_bf16 v[34:37], v[174:177], v[228:231], v[34:37]
	v_mfma_f32_16x16x32_bf16 v[26:29], v[166:169], v[236:239], v[26:29]
	v_mfma_f32_16x16x32_bf16 v[18:21], v[174:177], v[236:239], v[18:21]
	v_mfma_f32_16x16x32_bf16 v[10:13], v[166:169], v[244:247], v[10:13]
	v_mfma_f32_16x16x32_bf16 v[2:5], v[174:177], v[244:247], v[2:5]
	s_barrier
	s_add_i32 s10, 0, 0x18000
	s_add_i32 s11, 0, 0x1c000
	v_add_u32_e32 v158, s10, v143
	v_add_u32_e32 v174, s11, v143
	ds_read_b128 v[146:149], v158
	ds_read_b128 v[150:153], v158 offset:1024
	ds_read_b128 v[154:157], v158 offset:2048
	ds_read_b128 v[158:161], v158 offset:3072
	ds_read_b128 v[162:165], v174
	ds_read_b128 v[166:169], v174 offset:1024
	ds_read_b128 v[170:173], v174 offset:2048
	ds_read_b128 v[174:177], v174 offset:3072
	s_add_u32 s100, s54, 0x40000
	s_addc_u32 s101, s55, 0
	v_lshl_add_u64 v[250:251], s[100:101], 0, v[0:1]
	s_add_i32 m0, s52, 0x14000
	s_nop 0
	global_load_lds_dwordx4 v[250:251], off
	v_lshl_add_u64 v[250:251], s[100:101], 0, v[130:131]
	s_add_i32 m0, s52, 0x16000
	s_nop 0
	global_load_lds_dwordx4 v[250:251], off
	s_add_u32 s8, s56, 0x40000
	s_addc_u32 s9, s57, 0
	s_mov_b32 m0, s59
	v_lshl_add_u64 v[250:251], s[8:9], 0, v[134:135]
	ds_read_b128 v[178:181], v145 offset:32768
	ds_read_b128 v[182:185], v145 offset:33792
	ds_read_b128 v[224:227], v145 offset:34816
	ds_read_b128 v[228:231], v145 offset:35840
	ds_read_b128 v[232:235], v145 offset:36864
	ds_read_b128 v[236:239], v145 offset:37888
	ds_read_b128 v[240:243], v145 offset:38912
	ds_read_b128 v[244:247], v145 offset:39936
	global_load_lds_dwordx4 v[250:251], off
	v_lshl_add_u64 v[250:251], s[8:9], 0, v[132:133]
	s_mov_b32 m0, s60
	s_nop 0
	global_load_lds_dwordx4 v[250:251], off
	s_waitcnt vmcnt(8)
	s_waitcnt lgkmcnt(0)
	s_barrier
	s_waitcnt lgkmcnt(0)
	v_mfma_f32_16x16x32_bf16 v[126:129], v[146:149], v[178:181], v[126:129]
	v_mfma_f32_16x16x32_bf16 v[118:121], v[154:157], v[178:181], v[118:121]
	v_mfma_f32_16x16x32_bf16 v[110:113], v[146:149], v[224:227], v[110:113]
	v_mfma_f32_16x16x32_bf16 v[102:105], v[154:157], v[224:227], v[102:105]
	v_mfma_f32_16x16x32_bf16 v[94:97], v[146:149], v[232:235], v[94:97]
	v_mfma_f32_16x16x32_bf16 v[86:89], v[154:157], v[232:235], v[86:89]
	v_mfma_f32_16x16x32_bf16 v[78:81], v[146:149], v[240:243], v[78:81]
	v_mfma_f32_16x16x32_bf16 v[70:73], v[154:157], v[240:243], v[70:73]
	v_mfma_f32_16x16x32_bf16 v[126:129], v[150:153], v[182:185], v[126:129]
	v_mfma_f32_16x16x32_bf16 v[118:121], v[158:161], v[182:185], v[118:121]
	v_mfma_f32_16x16x32_bf16 v[110:113], v[150:153], v[228:231], v[110:113]
	v_mfma_f32_16x16x32_bf16 v[102:105], v[158:161], v[228:231], v[102:105]
	v_mfma_f32_16x16x32_bf16 v[94:97], v[150:153], v[236:239], v[94:97]
	v_mfma_f32_16x16x32_bf16 v[86:89], v[158:161], v[236:239], v[86:89]
	v_mfma_f32_16x16x32_bf16 v[78:81], v[150:153], v[244:247], v[78:81]
	v_mfma_f32_16x16x32_bf16 v[70:73], v[158:161], v[244:247], v[70:73]
	v_mfma_f32_16x16x32_bf16 v[122:125], v[162:165], v[178:181], v[122:125]
	v_mfma_f32_16x16x32_bf16 v[114:117], v[170:173], v[178:181], v[114:117]
	v_mfma_f32_16x16x32_bf16 v[106:109], v[162:165], v[224:227], v[106:109]
	v_mfma_f32_16x16x32_bf16 v[98:101], v[170:173], v[224:227], v[98:101]
	v_mfma_f32_16x16x32_bf16 v[90:93], v[162:165], v[232:235], v[90:93]
	v_mfma_f32_16x16x32_bf16 v[82:85], v[170:173], v[232:235], v[82:85]
	v_mfma_f32_16x16x32_bf16 v[74:77], v[162:165], v[240:243], v[74:77]
	v_mfma_f32_16x16x32_bf16 v[66:69], v[170:173], v[240:243], v[66:69]
	v_mfma_f32_16x16x32_bf16 v[122:125], v[166:169], v[182:185], v[122:125]
	v_mfma_f32_16x16x32_bf16 v[114:117], v[174:177], v[182:185], v[114:117]
	v_mfma_f32_16x16x32_bf16 v[106:109], v[166:169], v[228:231], v[106:109]
	v_mfma_f32_16x16x32_bf16 v[98:101], v[174:177], v[228:231], v[98:101]
	v_mfma_f32_16x16x32_bf16 v[90:93], v[166:169], v[236:239], v[90:93]
	v_mfma_f32_16x16x32_bf16 v[82:85], v[174:177], v[236:239], v[82:85]
	v_mfma_f32_16x16x32_bf16 v[74:77], v[166:169], v[244:247], v[74:77]
	v_mfma_f32_16x16x32_bf16 v[66:69], v[174:177], v[244:247], v[66:69]
	s_barrier
	s_add_i32 s8, s10, s52
	v_lshl_add_u64 v[140:141], v[140:141], 0, s[26:27]
	s_mov_b32 m0, s8
	ds_read_b128 v[178:181], v145 offset:49152
	ds_read_b128 v[182:185], v145 offset:50176
	ds_read_b128 v[224:227], v145 offset:51200
	ds_read_b128 v[228:231], v145 offset:52224
	ds_read_b128 v[232:235], v145 offset:53248
	ds_read_b128 v[236:239], v145 offset:54272
	ds_read_b128 v[240:243], v145 offset:55296
	ds_read_b128 v[244:247], v145 offset:56320
	global_load_lds_dwordx4 v[140:141], off
	s_add_i32 m0, s8, 0x2000
	s_add_u32 s100, s54, 0x40080
	s_addc_u32 s101, s55, 0
	v_lshl_add_u64 v[140:141], v[186:187], 0, s[26:27]
	global_load_lds_dwordx4 v[140:141], off
	v_lshl_add_u64 v[140:141], v[202:203], 0, s[26:27]
	s_mov_b32 m0, s61
	s_nop 0
	global_load_lds_dwordx4 v[140:141], off
	v_lshl_add_u64 v[140:141], v[248:249], 0, s[26:27]
	s_mov_b32 m0, s62
	s_nop 0
	global_load_lds_dwordx4 v[140:141], off
	s_waitcnt vmcnt(6)
	s_waitcnt lgkmcnt(0)
	s_barrier
	s_waitcnt lgkmcnt(0)
	v_mfma_f32_16x16x32_bf16 v[62:65], v[146:149], v[178:181], v[62:65]
	v_mfma_f32_16x16x32_bf16 v[54:57], v[154:157], v[178:181], v[54:57]
	v_mfma_f32_16x16x32_bf16 v[46:49], v[146:149], v[224:227], v[46:49]
	v_mfma_f32_16x16x32_bf16 v[38:41], v[154:157], v[224:227], v[38:41]
	v_mfma_f32_16x16x32_bf16 v[30:33], v[146:149], v[232:235], v[30:33]
	v_mfma_f32_16x16x32_bf16 v[22:25], v[154:157], v[232:235], v[22:25]
	v_mfma_f32_16x16x32_bf16 v[14:17], v[146:149], v[240:243], v[14:17]
	v_mfma_f32_16x16x32_bf16 v[6:9], v[154:157], v[240:243], v[6:9]
	v_mfma_f32_16x16x32_bf16 v[62:65], v[150:153], v[182:185], v[62:65]
	v_mfma_f32_16x16x32_bf16 v[54:57], v[158:161], v[182:185], v[54:57]
	v_mfma_f32_16x16x32_bf16 v[46:49], v[150:153], v[228:231], v[46:49]
	v_mfma_f32_16x16x32_bf16 v[38:41], v[158:161], v[228:231], v[38:41]
	v_mfma_f32_16x16x32_bf16 v[30:33], v[150:153], v[236:239], v[30:33]
	v_mfma_f32_16x16x32_bf16 v[22:25], v[158:161], v[236:239], v[22:25]
	v_mfma_f32_16x16x32_bf16 v[14:17], v[150:153], v[244:247], v[14:17]
	v_mfma_f32_16x16x32_bf16 v[6:9], v[158:161], v[244:247], v[6:9]
	v_mfma_f32_16x16x32_bf16 v[58:61], v[162:165], v[178:181], v[58:61]
	v_mfma_f32_16x16x32_bf16 v[50:53], v[170:173], v[178:181], v[50:53]
	v_mfma_f32_16x16x32_bf16 v[42:45], v[162:165], v[224:227], v[42:45]
	v_mfma_f32_16x16x32_bf16 v[34:37], v[170:173], v[224:227], v[34:37]
	v_mfma_f32_16x16x32_bf16 v[26:29], v[162:165], v[232:235], v[26:29]
	v_mfma_f32_16x16x32_bf16 v[18:21], v[170:173], v[232:235], v[18:21]
	v_mfma_f32_16x16x32_bf16 v[10:13], v[162:165], v[240:243], v[10:13]
	v_mfma_f32_16x16x32_bf16 v[2:5], v[170:173], v[240:243], v[2:5]
	v_mfma_f32_16x16x32_bf16 v[58:61], v[166:169], v[182:185], v[58:61]
	v_mfma_f32_16x16x32_bf16 v[50:53], v[174:177], v[182:185], v[50:53]
	v_mfma_f32_16x16x32_bf16 v[42:45], v[166:169], v[228:231], v[42:45]
	v_mfma_f32_16x16x32_bf16 v[34:37], v[174:177], v[228:231], v[34:37]
	v_mfma_f32_16x16x32_bf16 v[26:29], v[166:169], v[236:239], v[26:29]
	v_mfma_f32_16x16x32_bf16 v[18:21], v[174:177], v[236:239], v[18:21]
	v_mfma_f32_16x16x32_bf16 v[10:13], v[166:169], v[244:247], v[10:13]
	v_mfma_f32_16x16x32_bf16 v[2:5], v[174:177], v[244:247], v[2:5]
	s_barrier
	s_add_i32 s72, s72, 2
	s_add_u32 s50, s50, 0x100
	s_addc_u32 s51, s51, 0
	s_add_u32 s68, s68, 0x100
	s_addc_u32 s69, s69, 0
	s_cmp_gt_u32 s72, 13
	s_cbranch_scc0 .LBB0_120
	s_and_b64 vcc, exec, s[24:25]
	s_mov_b64 s[68:69], s[36:37]
	s_cbranch_vccz .LBB0_123
	s_barrier

.LBB0_535:
	s_add_u32 s56, s50, 0x100
	s_addc_u32 s57, s51, 0
	s_add_i32 s8, 0, 0x10000
	s_cmp_eq_u32 s74, 40
	s_cselect_b32 s59, s41, s57
	s_cselect_b32 s58, s40, s56
	v_add_u32_e32 v140, s8, v143
	s_cselect_b32 s55, s49, s73
	s_cselect_b32 s54, s48, s72
	s_add_i32 s10, 0, 0x14000
	ds_read_b128 v[146:149], v140
	ds_read_b128 v[150:153], v140 offset:1024
	ds_read_b128 v[154:157], v140 offset:2048
	ds_read_b128 v[158:161], v140 offset:3072
	v_add_u32_e32 v140, s10, v143
	ds_read_b128 v[162:165], v140
	ds_read_b128 v[166:169], v140 offset:1024
	ds_read_b128 v[170:173], v140 offset:2048
	ds_read_b128 v[174:177], v140 offset:3072
	v_lshl_add_u64 v[140:141], s[50:51], 0, v[136:137]
	s_add_i32 m0, s53, 0xc000
	ds_read_b128 v[178:181], v145
	ds_read_b128 v[182:185], v145 offset:1024
	ds_read_b128 v[224:227], v145 offset:2048
	ds_read_b128 v[228:231], v145 offset:3072
	ds_read_b128 v[232:235], v145 offset:4096
	ds_read_b128 v[236:239], v145 offset:5120
	ds_read_b128 v[240:243], v145 offset:6144
	ds_read_b128 v[244:247], v145 offset:7168
	global_load_lds_dwordx4 v[140:141], off
	v_lshl_add_u64 v[140:141], s[50:51], 0, v[138:139]
	s_add_i32 m0, s53, 0xe000
	s_nop 0
	global_load_lds_dwordx4 v[140:141], off
	s_waitcnt vmcnt(8)
	s_waitcnt lgkmcnt(0)
	s_barrier
	s_waitcnt lgkmcnt(0)
	v_mfma_f32_16x16x32_bf16 v[126:129], v[146:149], v[178:181], v[126:129]
	v_mfma_f32_16x16x32_bf16 v[122:125], v[154:157], v[178:181], v[122:125]
	v_mfma_f32_16x16x32_bf16 v[110:113], v[146:149], v[224:227], v[110:113]
	v_mfma_f32_16x16x32_bf16 v[106:109], v[154:157], v[224:227], v[106:109]
	v_mfma_f32_16x16x32_bf16 v[94:97], v[146:149], v[232:235], v[94:97]
	v_mfma_f32_16x16x32_bf16 v[90:93], v[154:157], v[232:235], v[90:93]
	v_mfma_f32_16x16x32_bf16 v[78:81], v[146:149], v[240:243], v[78:81]
	v_mfma_f32_16x16x32_bf16 v[74:77], v[154:157], v[240:243], v[74:77]
	v_mfma_f32_16x16x32_bf16 v[126:129], v[150:153], v[182:185], v[126:129]
	v_mfma_f32_16x16x32_bf16 v[122:125], v[158:161], v[182:185], v[122:125]
	v_mfma_f32_16x16x32_bf16 v[110:113], v[150:153], v[228:231], v[110:113]
	v_mfma_f32_16x16x32_bf16 v[106:109], v[158:161], v[228:231], v[106:109]
	v_mfma_f32_16x16x32_bf16 v[94:97], v[150:153], v[236:239], v[94:97]
	v_mfma_f32_16x16x32_bf16 v[90:93], v[158:161], v[236:239], v[90:93]
	v_mfma_f32_16x16x32_bf16 v[78:81], v[150:153], v[244:247], v[78:81]
	v_mfma_f32_16x16x32_bf16 v[74:77], v[158:161], v[244:247], v[74:77]
	v_mfma_f32_16x16x32_bf16 v[118:121], v[162:165], v[178:181], v[118:121]
	v_mfma_f32_16x16x32_bf16 v[114:117], v[170:173], v[178:181], v[114:117]
	v_mfma_f32_16x16x32_bf16 v[102:105], v[162:165], v[224:227], v[102:105]
	v_mfma_f32_16x16x32_bf16 v[98:101], v[170:173], v[224:227], v[98:101]
	v_mfma_f32_16x16x32_bf16 v[86:89], v[162:165], v[232:235], v[86:89]
	v_mfma_f32_16x16x32_bf16 v[82:85], v[170:173], v[232:235], v[82:85]
	v_mfma_f32_16x16x32_bf16 v[70:73], v[162:165], v[240:243], v[70:73]
	v_mfma_f32_16x16x32_bf16 v[66:69], v[170:173], v[240:243], v[66:69]
	v_mfma_f32_16x16x32_bf16 v[118:121], v[166:169], v[182:185], v[118:121]
	v_mfma_f32_16x16x32_bf16 v[114:117], v[174:177], v[182:185], v[114:117]
	v_mfma_f32_16x16x32_bf16 v[102:105], v[166:169], v[228:231], v[102:105]
	v_mfma_f32_16x16x32_bf16 v[98:101], v[174:177], v[228:231], v[98:101]
	v_mfma_f32_16x16x32_bf16 v[86:89], v[166:169], v[236:239], v[86:89]
	v_mfma_f32_16x16x32_bf16 v[82:85], v[174:177], v[236:239], v[82:85]
	v_mfma_f32_16x16x32_bf16 v[70:73], v[166:169], v[244:247], v[70:73]
	v_mfma_f32_16x16x32_bf16 v[66:69], v[174:177], v[244:247], v[66:69]
	s_barrier
	s_add_i32 s8, s8, s52
	v_lshl_add_u64 v[140:141], s[54:55], 0, v[0:1]
	s_mov_b32 m0, s8
	ds_read_b128 v[178:181], v145 offset:16384
	ds_read_b128 v[182:185], v145 offset:17408
	ds_read_b128 v[224:227], v145 offset:18432
	ds_read_b128 v[228:231], v145 offset:19456
	ds_read_b128 v[232:235], v145 offset:20480
	ds_read_b128 v[236:239], v145 offset:21504
	ds_read_b128 v[240:243], v145 offset:22528
	ds_read_b128 v[244:247], v145 offset:23552
	global_load_lds_dwordx4 v[140:141], off
	s_add_i32 m0, s8, 0x2000
	s_add_u32 s8, s54, 0xb0000
	v_lshl_add_u64 v[186:187], s[54:55], 0, v[130:131]
	s_addc_u32 s9, s55, 0
	s_add_i32 s10, s10, s52
	global_load_lds_dwordx4 v[186:187], off
	v_lshl_add_u64 v[202:203], s[8:9], 0, v[0:1]
	s_mov_b32 m0, s10
	v_lshl_add_u64 v[248:249], s[58:59], 0, v[132:133]
	global_load_lds_dwordx4 v[202:203], off
	v_lshl_add_u64 v[202:203], s[8:9], 0, v[130:131]
	s_add_i32 m0, s10, 0x2000
	s_nop 0
	global_load_lds_dwordx4 v[202:203], off
	v_lshl_add_u64 v[202:203], s[58:59], 0, v[134:135]
	s_mov_b32 m0, s53
	s_nop 0
	global_load_lds_dwordx4 v[202:203], off
	s_mov_b32 m0, s60
	s_nop 0
	global_load_lds_dwordx4 v[248:249], off
	s_waitcnt vmcnt(8)
	s_waitcnt lgkmcnt(0)
	s_barrier
	s_waitcnt lgkmcnt(0)
	v_mfma_f32_16x16x32_bf16 v[62:65], v[146:149], v[178:181], v[62:65]
	v_mfma_f32_16x16x32_bf16 v[58:61], v[154:157], v[178:181], v[58:61]
	v_mfma_f32_16x16x32_bf16 v[46:49], v[146:149], v[224:227], v[46:49]
	v_mfma_f32_16x16x32_bf16 v[42:45], v[154:157], v[224:227], v[42:45]
	v_mfma_f32_16x16x32_bf16 v[30:33], v[146:149], v[232:235], v[30:33]
	v_mfma_f32_16x16x32_bf16 v[26:29], v[154:157], v[232:235], v[26:29]
	v_mfma_f32_16x16x32_bf16 v[14:17], v[146:149], v[240:243], v[14:17]
	v_mfma_f32_16x16x32_bf16 v[10:13], v[154:157], v[240:243], v[10:13]
	v_mfma_f32_16x16x32_bf16 v[62:65], v[150:153], v[182:185], v[62:65]
	v_mfma_f32_16x16x32_bf16 v[58:61], v[158:161], v[182:185], v[58:61]
	v_mfma_f32_16x16x32_bf16 v[46:49], v[150:153], v[228:231], v[46:49]
	v_mfma_f32_16x16x32_bf16 v[42:45], v[158:161], v[228:231], v[42:45]
	v_mfma_f32_16x16x32_bf16 v[30:33], v[150:153], v[236:239], v[30:33]
	v_mfma_f32_16x16x32_bf16 v[26:29], v[158:161], v[236:239], v[26:29]
	v_mfma_f32_16x16x32_bf16 v[14:17], v[150:153], v[244:247], v[14:17]
	v_mfma_f32_16x16x32_bf16 v[10:13], v[158:161], v[244:247], v[10:13]
	v_mfma_f32_16x16x32_bf16 v[54:57], v[162:165], v[178:181], v[54:57]
	v_mfma_f32_16x16x32_bf16 v[50:53], v[170:173], v[178:181], v[50:53]
	v_mfma_f32_16x16x32_bf16 v[38:41], v[162:165], v[224:227], v[38:41]
	v_mfma_f32_16x16x32_bf16 v[34:37], v[170:173], v[224:227], v[34:37]
	v_mfma_f32_16x16x32_bf16 v[22:25], v[162:165], v[232:235], v[22:25]
	v_mfma_f32_16x16x32_bf16 v[18:21], v[170:173], v[232:235], v[18:21]
	v_mfma_f32_16x16x32_bf16 v[6:9], v[162:165], v[240:243], v[6:9]
	v_mfma_f32_16x16x32_bf16 v[2:5], v[170:173], v[240:243], v[2:5]
	v_mfma_f32_16x16x32_bf16 v[54:57], v[166:169], v[182:185], v[54:57]
	v_mfma_f32_16x16x32_bf16 v[50:53], v[174:177], v[182:185], v[50:53]
	v_mfma_f32_16x16x32_bf16 v[38:41], v[166:169], v[228:231], v[38:41]
	v_mfma_f32_16x16x32_bf16 v[34:37], v[174:177], v[228:231], v[34:37]
	v_mfma_f32_16x16x32_bf16 v[22:25], v[166:169], v[236:239], v[22:25]
	v_mfma_f32_16x16x32_bf16 v[18:21], v[174:177], v[236:239], v[18:21]
	v_mfma_f32_16x16x32_bf16 v[6:9], v[166:169], v[244:247], v[6:9]
	v_mfma_f32_16x16x32_bf16 v[2:5], v[174:177], v[244:247], v[2:5]
	s_barrier
	s_add_i32 s10, 0, 0x18000
	s_add_i32 s11, 0, 0x1c000
	v_add_u32_e32 v158, s10, v143
	v_add_u32_e32 v174, s11, v143
	ds_read_b128 v[146:149], v158
	ds_read_b128 v[150:153], v158 offset:1024
	ds_read_b128 v[154:157], v158 offset:2048
	ds_read_b128 v[158:161], v158 offset:3072
	ds_read_b128 v[162:165], v174
	ds_read_b128 v[166:169], v174 offset:1024
	ds_read_b128 v[170:173], v174 offset:2048
	ds_read_b128 v[174:177], v174 offset:3072
	s_add_u32 s8, s58, 0xb0000
	s_addc_u32 s9, s59, 0
	s_mov_b32 m0, s61
	v_lshl_add_u64 v[250:251], s[8:9], 0, v[134:135]
	ds_read_b128 v[178:181], v145 offset:32768
	ds_read_b128 v[182:185], v145 offset:33792
	ds_read_b128 v[224:227], v145 offset:34816
	ds_read_b128 v[228:231], v145 offset:35840
	ds_read_b128 v[232:235], v145 offset:36864
	ds_read_b128 v[236:239], v145 offset:37888
	ds_read_b128 v[240:243], v145 offset:38912
	ds_read_b128 v[244:247], v145 offset:39936
	global_load_lds_dwordx4 v[250:251], off
	v_lshl_add_u64 v[250:251], s[8:9], 0, v[132:133]
	s_mov_b32 m0, s62
	s_nop 0
	global_load_lds_dwordx4 v[250:251], off
	s_waitcnt vmcnt(8)
	s_waitcnt lgkmcnt(0)
	s_barrier
	s_waitcnt lgkmcnt(0)
	v_mfma_f32_16x16x32_bf16 v[126:129], v[146:149], v[178:181], v[126:129]
	v_mfma_f32_16x16x32_bf16 v[122:125], v[154:157], v[178:181], v[122:125]
	v_mfma_f32_16x16x32_bf16 v[110:113], v[146:149], v[224:227], v[110:113]
	v_mfma_f32_16x16x32_bf16 v[106:109], v[154:157], v[224:227], v[106:109]
	v_mfma_f32_16x16x32_bf16 v[94:97], v[146:149], v[232:235], v[94:97]
	v_mfma_f32_16x16x32_bf16 v[90:93], v[154:157], v[232:235], v[90:93]
	v_mfma_f32_16x16x32_bf16 v[78:81], v[146:149], v[240:243], v[78:81]
	v_mfma_f32_16x16x32_bf16 v[74:77], v[154:157], v[240:243], v[74:77]
	v_mfma_f32_16x16x32_bf16 v[126:129], v[150:153], v[182:185], v[126:129]
	v_mfma_f32_16x16x32_bf16 v[122:125], v[158:161], v[182:185], v[122:125]
	v_mfma_f32_16x16x32_bf16 v[110:113], v[150:153], v[228:231], v[110:113]
	v_mfma_f32_16x16x32_bf16 v[106:109], v[158:161], v[228:231], v[106:109]
	v_mfma_f32_16x16x32_bf16 v[94:97], v[150:153], v[236:239], v[94:97]
	v_mfma_f32_16x16x32_bf16 v[90:93], v[158:161], v[236:239], v[90:93]
	v_mfma_f32_16x16x32_bf16 v[78:81], v[150:153], v[244:247], v[78:81]
	v_mfma_f32_16x16x32_bf16 v[74:77], v[158:161], v[244:247], v[74:77]
	v_mfma_f32_16x16x32_bf16 v[118:121], v[162:165], v[178:181], v[118:121]
	v_mfma_f32_16x16x32_bf16 v[114:117], v[170:173], v[178:181], v[114:117]
	v_mfma_f32_16x16x32_bf16 v[102:105], v[162:165], v[224:227], v[102:105]
	v_mfma_f32_16x16x32_bf16 v[98:101], v[170:173], v[224:227], v[98:101]
	v_mfma_f32_16x16x32_bf16 v[86:89], v[162:165], v[232:235], v[86:89]
	v_mfma_f32_16x16x32_bf16 v[82:85], v[170:173], v[232:235], v[82:85]
	v_mfma_f32_16x16x32_bf16 v[70:73], v[162:165], v[240:243], v[70:73]
	v_mfma_f32_16x16x32_bf16 v[66:69], v[170:173], v[240:243], v[66:69]
	v_mfma_f32_16x16x32_bf16 v[118:121], v[166:169], v[182:185], v[118:121]
	v_mfma_f32_16x16x32_bf16 v[114:117], v[174:177], v[182:185], v[114:117]
	v_mfma_f32_16x16x32_bf16 v[102:105], v[166:169], v[228:231], v[102:105]
	v_mfma_f32_16x16x32_bf16 v[98:101], v[174:177], v[228:231], v[98:101]
	v_mfma_f32_16x16x32_bf16 v[86:89], v[166:169], v[236:239], v[86:89]
	v_mfma_f32_16x16x32_bf16 v[82:85], v[174:177], v[236:239], v[82:85]
	v_mfma_f32_16x16x32_bf16 v[70:73], v[166:169], v[244:247], v[70:73]
	v_mfma_f32_16x16x32_bf16 v[66:69], v[174:177], v[244:247], v[66:69]
	s_barrier
	s_add_i32 s8, s10, s52
	v_lshl_add_u64 v[140:141], v[140:141], 0, s[26:27]
	s_mov_b32 m0, s8
	ds_read_b128 v[178:181], v145 offset:49152
	ds_read_b128 v[182:185], v145 offset:50176
	ds_read_b128 v[224:227], v145 offset:51200
	ds_read_b128 v[228:231], v145 offset:52224
	ds_read_b128 v[232:235], v145 offset:53248
	ds_read_b128 v[236:239], v145 offset:54272
	ds_read_b128 v[240:243], v145 offset:55296
	ds_read_b128 v[244:247], v145 offset:56320
	global_load_lds_dwordx4 v[140:141], off
	s_add_i32 m0, s8, 0x2000
	s_add_u32 s8, s54, 0xb0080
	v_lshl_add_u64 v[140:141], v[186:187], 0, s[26:27]
	s_addc_u32 s9, s55, 0
	s_add_i32 s10, s11, s52
	global_load_lds_dwordx4 v[140:141], off
	v_lshl_add_u64 v[140:141], s[8:9], 0, v[0:1]
	s_mov_b32 m0, s10
	s_nop 0
	global_load_lds_dwordx4 v[140:141], off
	v_lshl_add_u64 v[140:141], s[8:9], 0, v[130:131]
	s_add_i32 m0, s10, 0x2000
	s_nop 0
	global_load_lds_dwordx4 v[140:141], off
	v_lshl_add_u64 v[140:141], v[202:203], 0, s[26:27]
	s_mov_b32 m0, s63
	s_nop 0
	global_load_lds_dwordx4 v[140:141], off
	v_lshl_add_u64 v[140:141], v[248:249], 0, s[26:27]
	s_mov_b32 m0, s64
	s_nop 0
	global_load_lds_dwordx4 v[140:141], off
	s_waitcnt vmcnt(8)
	s_waitcnt lgkmcnt(0)
	s_barrier
	s_waitcnt lgkmcnt(0)
	v_mfma_f32_16x16x32_bf16 v[62:65], v[146:149], v[178:181], v[62:65]
	v_mfma_f32_16x16x32_bf16 v[58:61], v[154:157], v[178:181], v[58:61]
	v_mfma_f32_16x16x32_bf16 v[46:49], v[146:149], v[224:227], v[46:49]
	v_mfma_f32_16x16x32_bf16 v[42:45], v[154:157], v[224:227], v[42:45]
	v_mfma_f32_16x16x32_bf16 v[30:33], v[146:149], v[232:235], v[30:33]
	v_mfma_f32_16x16x32_bf16 v[26:29], v[154:157], v[232:235], v[26:29]
	v_mfma_f32_16x16x32_bf16 v[14:17], v[146:149], v[240:243], v[14:17]
	v_mfma_f32_16x16x32_bf16 v[10:13], v[154:157], v[240:243], v[10:13]
	v_mfma_f32_16x16x32_bf16 v[62:65], v[150:153], v[182:185], v[62:65]
	v_mfma_f32_16x16x32_bf16 v[58:61], v[158:161], v[182:185], v[58:61]
	v_mfma_f32_16x16x32_bf16 v[46:49], v[150:153], v[228:231], v[46:49]
	v_mfma_f32_16x16x32_bf16 v[42:45], v[158:161], v[228:231], v[42:45]
	v_mfma_f32_16x16x32_bf16 v[30:33], v[150:153], v[236:239], v[30:33]
	v_mfma_f32_16x16x32_bf16 v[26:29], v[158:161], v[236:239], v[26:29]
	v_mfma_f32_16x16x32_bf16 v[14:17], v[150:153], v[244:247], v[14:17]
	v_mfma_f32_16x16x32_bf16 v[10:13], v[158:161], v[244:247], v[10:13]
	v_mfma_f32_16x16x32_bf16 v[54:57], v[162:165], v[178:181], v[54:57]
	v_mfma_f32_16x16x32_bf16 v[50:53], v[170:173], v[178:181], v[50:53]
	v_mfma_f32_16x16x32_bf16 v[38:41], v[162:165], v[224:227], v[38:41]
	v_mfma_f32_16x16x32_bf16 v[34:37], v[170:173], v[224:227], v[34:37]
	v_mfma_f32_16x16x32_bf16 v[22:25], v[162:165], v[232:235], v[22:25]
	v_mfma_f32_16x16x32_bf16 v[18:21], v[170:173], v[232:235], v[18:21]
	v_mfma_f32_16x16x32_bf16 v[6:9], v[162:165], v[240:243], v[6:9]
	v_mfma_f32_16x16x32_bf16 v[2:5], v[170:173], v[240:243], v[2:5]
	v_mfma_f32_16x16x32_bf16 v[54:57], v[166:169], v[182:185], v[54:57]
	v_mfma_f32_16x16x32_bf16 v[50:53], v[174:177], v[182:185], v[50:53]
	v_mfma_f32_16x16x32_bf16 v[38:41], v[166:169], v[228:231], v[38:41]
	v_mfma_f32_16x16x32_bf16 v[34:37], v[174:177], v[228:231], v[34:37]
	v_mfma_f32_16x16x32_bf16 v[22:25], v[166:169], v[236:239], v[22:25]
	v_mfma_f32_16x16x32_bf16 v[18:21], v[174:177], v[236:239], v[18:21]
	v_mfma_f32_16x16x32_bf16 v[6:9], v[166:169], v[244:247], v[6:9]
	v_mfma_f32_16x16x32_bf16 v[2:5], v[174:177], v[244:247], v[2:5]
	s_barrier
	s_add_i32 s74, s74, 2
	s_add_u32 s72, s72, 0x100
	s_addc_u32 s73, s73, 0
	s_cmp_gt_u32 s74, 41
	s_mov_b64 s[50:51], s[56:57]
	s_cbranch_scc0 .LBB0_535
	s_and_b64 vcc, exec, s[46:47]
	s_cbranch_vccz .LBB0_538
	s_barrier

.LBB0_546:
	s_add_i32 s10, s44, 0x100
	s_and_b64 s[8:9], s[42:43], exec
	s_cselect_b32 s9, 0, s10
	s_cselect_b32 s8, 0, 0
	s_add_u32 s46, s82, s9
	s_addc_u32 s47, s83, s8
	s_add_i32 s10, 0, 0x10000
	s_add_u32 s48, s38, s9
	s_addc_u32 s49, s39, s8
	s_add_i32 s8, 0, 0x14000
	s_add_u32 s54, s34, s44
	s_addc_u32 s55, s35, 0
	s_add_i32 s68, s10, s53
	s_add_i32 m0, s4, 0xc000
	s_add_i32 s9, s4, 0xe000
	s_add_i32 s65, s68, 0x2000
	s_add_u32 s50, s48, 0xb0000
	v_add_u32_e32 v148, s10, v134
	v_add_u32_e32 v164, s8, v134
	s_addc_u32 s51, s49, 0
	s_add_i32 s67, s8, s53
	ds_read_b128 v[136:139], v148
	ds_read_b128 v[140:143], v148 offset:1024
	ds_read_b128 v[144:147], v148 offset:2048
	ds_read_b128 v[148:151], v148 offset:3072
	ds_read_b128 v[152:155], v164
	ds_read_b128 v[156:159], v164 offset:1024
	ds_read_b128 v[160:163], v164 offset:2048
	ds_read_b128 v[164:167], v164 offset:3072
	s_add_i32 s66, s67, 0x2000
	s_add_i32 s64, 0, 0x18000
	s_add_i32 s63, 0, 0x1c000
	s_add_u32 s44, s46, 0xb0000
	s_addc_u32 s45, s47, 0
	s_add_i32 s62, s64, s53
	s_add_i32 s61, s62, 0x2000
	s_add_u32 s42, s48, 0xb0080
	s_addc_u32 s43, s49, 0
	s_add_i32 s72, s63, s53
	s_add_i32 s69, s72, 0x2000
	v_lshl_add_u64 v[202:203], s[54:55], 0, v[0:1]
	v_lshl_add_u64 v[202:203], v[202:203], 0, s[26:27]
	ds_read_b128 v[168:171], v135
	ds_read_b128 v[172:175], v135 offset:1024
	ds_read_b128 v[176:179], v135 offset:2048
	ds_read_b128 v[180:183], v135 offset:3072
	ds_read_b128 v[184:187], v135 offset:4096
	ds_read_b128 v[224:227], v135 offset:5120
	ds_read_b128 v[228:231], v135 offset:6144
	ds_read_b128 v[232:235], v135 offset:7168
	global_load_lds_dwordx4 v[202:203], off
	v_lshl_add_u64 v[202:203], s[54:55], 0, v[130:131]
	v_lshl_add_u64 v[202:203], v[202:203], 0, s[26:27]
	s_mov_b32 m0, s9
	s_nop 0
	global_load_lds_dwordx4 v[202:203], off
	s_waitcnt vmcnt(8)
	s_waitcnt lgkmcnt(0)
	s_barrier
	s_waitcnt lgkmcnt(0)
	v_mfma_f32_16x16x32_bf16 v[126:129], v[136:139], v[168:171], v[126:129]
	v_mfma_f32_16x16x32_bf16 v[122:125], v[144:147], v[168:171], v[122:125]
	v_mfma_f32_16x16x32_bf16 v[118:121], v[136:139], v[176:179], v[118:121]
	v_mfma_f32_16x16x32_bf16 v[110:113], v[144:147], v[176:179], v[110:113]
	v_mfma_f32_16x16x32_bf16 v[102:105], v[136:139], v[184:187], v[102:105]
	v_mfma_f32_16x16x32_bf16 v[94:97], v[144:147], v[184:187], v[94:97]
	v_mfma_f32_16x16x32_bf16 v[86:89], v[136:139], v[228:231], v[86:89]
	v_mfma_f32_16x16x32_bf16 v[78:81], v[144:147], v[228:231], v[78:81]
	v_mfma_f32_16x16x32_bf16 v[126:129], v[140:143], v[172:175], v[126:129]
	v_mfma_f32_16x16x32_bf16 v[122:125], v[148:151], v[172:175], v[122:125]
	v_mfma_f32_16x16x32_bf16 v[118:121], v[140:143], v[180:183], v[118:121]
	v_mfma_f32_16x16x32_bf16 v[110:113], v[148:151], v[180:183], v[110:113]
	v_mfma_f32_16x16x32_bf16 v[102:105], v[140:143], v[224:227], v[102:105]
	v_mfma_f32_16x16x32_bf16 v[94:97], v[148:151], v[224:227], v[94:97]
	v_mfma_f32_16x16x32_bf16 v[86:89], v[140:143], v[232:235], v[86:89]
	v_mfma_f32_16x16x32_bf16 v[78:81], v[148:151], v[232:235], v[78:81]
	v_mfma_f32_16x16x32_bf16 v[114:117], v[152:155], v[168:171], v[114:117]
	v_mfma_f32_16x16x32_bf16 v[106:109], v[160:163], v[168:171], v[106:109]
	v_mfma_f32_16x16x32_bf16 v[98:101], v[152:155], v[176:179], v[98:101]
	v_mfma_f32_16x16x32_bf16 v[90:93], v[160:163], v[176:179], v[90:93]
	v_mfma_f32_16x16x32_bf16 v[82:85], v[152:155], v[184:187], v[82:85]
	v_mfma_f32_16x16x32_bf16 v[74:77], v[160:163], v[184:187], v[74:77]
	v_mfma_f32_16x16x32_bf16 v[70:73], v[152:155], v[228:231], v[70:73]
	v_mfma_f32_16x16x32_bf16 v[66:69], v[160:163], v[228:231], v[66:69]
	v_mfma_f32_16x16x32_bf16 v[114:117], v[156:159], v[172:175], v[114:117]
	v_mfma_f32_16x16x32_bf16 v[106:109], v[164:167], v[172:175], v[106:109]
	v_mfma_f32_16x16x32_bf16 v[98:101], v[156:159], v[180:183], v[98:101]
	v_mfma_f32_16x16x32_bf16 v[90:93], v[164:167], v[180:183], v[90:93]
	v_mfma_f32_16x16x32_bf16 v[82:85], v[156:159], v[224:227], v[82:85]
	v_mfma_f32_16x16x32_bf16 v[74:77], v[164:167], v[224:227], v[74:77]
	v_mfma_f32_16x16x32_bf16 v[70:73], v[156:159], v[232:235], v[70:73]
	v_mfma_f32_16x16x32_bf16 v[66:69], v[164:167], v[232:235], v[66:69]
	s_barrier
	s_mov_b32 m0, s68
	v_lshl_add_u64 v[202:203], s[48:49], 0, v[0:1]
	ds_read_b128 v[168:171], v135 offset:16384
	ds_read_b128 v[172:175], v135 offset:17408
	ds_read_b128 v[176:179], v135 offset:18432
	ds_read_b128 v[180:183], v135 offset:19456
	ds_read_b128 v[184:187], v135 offset:20480
	ds_read_b128 v[224:227], v135 offset:21504
	ds_read_b128 v[228:231], v135 offset:22528
	ds_read_b128 v[232:235], v135 offset:23552
	global_load_lds_dwordx4 v[202:203], off
	v_lshl_add_u64 v[236:237], s[48:49], 0, v[130:131]
	s_mov_b32 m0, s65
	v_lshl_add_u64 v[238:239], s[50:51], 0, v[0:1]
	global_load_lds_dwordx4 v[236:237], off
	s_mov_b32 m0, s67
	v_lshl_add_u64 v[240:241], s[46:47], 0, v[130:131]
	global_load_lds_dwordx4 v[238:239], off
	v_lshl_add_u64 v[238:239], s[50:51], 0, v[130:131]
	s_mov_b32 m0, s66
	s_nop 0
	global_load_lds_dwordx4 v[238:239], off
	v_lshl_add_u64 v[238:239], s[46:47], 0, v[0:1]
	s_mov_b32 m0, s4
	s_nop 0
	global_load_lds_dwordx4 v[238:239], off
	s_mov_b32 m0, s5
	s_nop 0
	global_load_lds_dwordx4 v[240:241], off
	s_waitcnt vmcnt(8)
	s_waitcnt lgkmcnt(0)
	s_barrier
	s_waitcnt lgkmcnt(0)
	v_mfma_f32_16x16x32_bf16 v[62:65], v[136:139], v[168:171], v[62:65]
	v_mfma_f32_16x16x32_bf16 v[58:61], v[144:147], v[168:171], v[58:61]
	v_mfma_f32_16x16x32_bf16 v[54:57], v[136:139], v[176:179], v[54:57]
	v_mfma_f32_16x16x32_bf16 v[46:49], v[144:147], v[176:179], v[46:49]
	v_mfma_f32_16x16x32_bf16 v[38:41], v[136:139], v[184:187], v[38:41]
	v_mfma_f32_16x16x32_bf16 v[30:33], v[144:147], v[184:187], v[30:33]
	v_mfma_f32_16x16x32_bf16 v[22:25], v[136:139], v[228:231], v[22:25]
	v_mfma_f32_16x16x32_bf16 v[14:17], v[144:147], v[228:231], v[14:17]
	v_mfma_f32_16x16x32_bf16 v[62:65], v[140:143], v[172:175], v[62:65]
	v_mfma_f32_16x16x32_bf16 v[58:61], v[148:151], v[172:175], v[58:61]
	v_mfma_f32_16x16x32_bf16 v[54:57], v[140:143], v[180:183], v[54:57]
	v_mfma_f32_16x16x32_bf16 v[46:49], v[148:151], v[180:183], v[46:49]
	v_mfma_f32_16x16x32_bf16 v[38:41], v[140:143], v[224:227], v[38:41]
	v_mfma_f32_16x16x32_bf16 v[30:33], v[148:151], v[224:227], v[30:33]
	v_mfma_f32_16x16x32_bf16 v[22:25], v[140:143], v[232:235], v[22:25]
	v_mfma_f32_16x16x32_bf16 v[14:17], v[148:151], v[232:235], v[14:17]
	v_mfma_f32_16x16x32_bf16 v[50:53], v[152:155], v[168:171], v[50:53]
	v_mfma_f32_16x16x32_bf16 v[42:45], v[160:163], v[168:171], v[42:45]
	v_mfma_f32_16x16x32_bf16 v[34:37], v[152:155], v[176:179], v[34:37]
	v_mfma_f32_16x16x32_bf16 v[26:29], v[160:163], v[176:179], v[26:29]
	v_mfma_f32_16x16x32_bf16 v[18:21], v[152:155], v[184:187], v[18:21]
	v_mfma_f32_16x16x32_bf16 v[10:13], v[160:163], v[184:187], v[10:13]
	v_mfma_f32_16x16x32_bf16 v[6:9], v[152:155], v[228:231], v[6:9]
	v_mfma_f32_16x16x32_bf16 v[2:5], v[160:163], v[228:231], v[2:5]
	v_mfma_f32_16x16x32_bf16 v[50:53], v[156:159], v[172:175], v[50:53]
	v_mfma_f32_16x16x32_bf16 v[42:45], v[164:167], v[172:175], v[42:45]
	v_mfma_f32_16x16x32_bf16 v[34:37], v[156:159], v[180:183], v[34:37]
	v_mfma_f32_16x16x32_bf16 v[26:29], v[164:167], v[180:183], v[26:29]
	v_mfma_f32_16x16x32_bf16 v[18:21], v[156:159], v[224:227], v[18:21]
	v_mfma_f32_16x16x32_bf16 v[10:13], v[164:167], v[224:227], v[10:13]
	v_mfma_f32_16x16x32_bf16 v[6:9], v[156:159], v[232:235], v[6:9]
	v_mfma_f32_16x16x32_bf16 v[2:5], v[164:167], v[232:235], v[2:5]
	s_barrier
	v_add_u32_e32 v148, s64, v134
	v_add_u32_e32 v164, s63, v134
	ds_read_b128 v[136:139], v148
	ds_read_b128 v[140:143], v148 offset:1024
	ds_read_b128 v[144:147], v148 offset:2048
	ds_read_b128 v[148:151], v148 offset:3072
	ds_read_b128 v[152:155], v164
	ds_read_b128 v[156:159], v164 offset:1024
	ds_read_b128 v[160:163], v164 offset:2048
	ds_read_b128 v[164:167], v164 offset:3072
	s_mov_b32 m0, s56
	v_lshl_add_u64 v[242:243], s[44:45], 0, v[0:1]
	ds_read_b128 v[168:171], v135 offset:32768
	ds_read_b128 v[172:175], v135 offset:33792
	ds_read_b128 v[176:179], v135 offset:34816
	ds_read_b128 v[180:183], v135 offset:35840
	ds_read_b128 v[184:187], v135 offset:36864
	ds_read_b128 v[224:227], v135 offset:37888
	ds_read_b128 v[228:231], v135 offset:38912
	ds_read_b128 v[232:235], v135 offset:39936
	global_load_lds_dwordx4 v[242:243], off
	v_lshl_add_u64 v[242:243], s[44:45], 0, v[130:131]
	s_mov_b32 m0, s57
	s_nop 0
	global_load_lds_dwordx4 v[242:243], off
	s_waitcnt vmcnt(8)
	s_waitcnt lgkmcnt(0)
	s_barrier
	s_waitcnt lgkmcnt(0)
	v_mfma_f32_16x16x32_bf16 v[126:129], v[136:139], v[168:171], v[126:129]
	v_mfma_f32_16x16x32_bf16 v[122:125], v[144:147], v[168:171], v[122:125]
	v_mfma_f32_16x16x32_bf16 v[118:121], v[136:139], v[176:179], v[118:121]
	v_mfma_f32_16x16x32_bf16 v[110:113], v[144:147], v[176:179], v[110:113]
	v_mfma_f32_16x16x32_bf16 v[102:105], v[136:139], v[184:187], v[102:105]
	v_mfma_f32_16x16x32_bf16 v[94:97], v[144:147], v[184:187], v[94:97]
	v_mfma_f32_16x16x32_bf16 v[86:89], v[136:139], v[228:231], v[86:89]
	v_mfma_f32_16x16x32_bf16 v[78:81], v[144:147], v[228:231], v[78:81]
	v_mfma_f32_16x16x32_bf16 v[126:129], v[140:143], v[172:175], v[126:129]
	v_mfma_f32_16x16x32_bf16 v[122:125], v[148:151], v[172:175], v[122:125]
	v_mfma_f32_16x16x32_bf16 v[118:121], v[140:143], v[180:183], v[118:121]
	v_mfma_f32_16x16x32_bf16 v[110:113], v[148:151], v[180:183], v[110:113]
	v_mfma_f32_16x16x32_bf16 v[102:105], v[140:143], v[224:227], v[102:105]
	v_mfma_f32_16x16x32_bf16 v[94:97], v[148:151], v[224:227], v[94:97]
	v_mfma_f32_16x16x32_bf16 v[86:89], v[140:143], v[232:235], v[86:89]
	v_mfma_f32_16x16x32_bf16 v[78:81], v[148:151], v[232:235], v[78:81]
	v_mfma_f32_16x16x32_bf16 v[114:117], v[152:155], v[168:171], v[114:117]
	v_mfma_f32_16x16x32_bf16 v[106:109], v[160:163], v[168:171], v[106:109]
	v_mfma_f32_16x16x32_bf16 v[98:101], v[152:155], v[176:179], v[98:101]
	v_mfma_f32_16x16x32_bf16 v[90:93], v[160:163], v[176:179], v[90:93]
	v_mfma_f32_16x16x32_bf16 v[82:85], v[152:155], v[184:187], v[82:85]
	v_mfma_f32_16x16x32_bf16 v[74:77], v[160:163], v[184:187], v[74:77]
	v_mfma_f32_16x16x32_bf16 v[70:73], v[152:155], v[228:231], v[70:73]
	v_mfma_f32_16x16x32_bf16 v[66:69], v[160:163], v[228:231], v[66:69]
	v_mfma_f32_16x16x32_bf16 v[114:117], v[156:159], v[172:175], v[114:117]
	v_mfma_f32_16x16x32_bf16 v[106:109], v[164:167], v[172:175], v[106:109]
	v_mfma_f32_16x16x32_bf16 v[98:101], v[156:159], v[180:183], v[98:101]
	v_mfma_f32_16x16x32_bf16 v[90:93], v[164:167], v[180:183], v[90:93]
	v_mfma_f32_16x16x32_bf16 v[82:85], v[156:159], v[224:227], v[82:85]
	v_mfma_f32_16x16x32_bf16 v[74:77], v[164:167], v[224:227], v[74:77]
	v_mfma_f32_16x16x32_bf16 v[70:73], v[156:159], v[232:235], v[70:73]
	v_mfma_f32_16x16x32_bf16 v[66:69], v[164:167], v[232:235], v[66:69]
	s_barrier
	s_mov_b32 m0, s62
	v_lshl_add_u64 v[202:203], v[202:203], 0, s[26:27]
	ds_read_b128 v[168:171], v135 offset:49152
	ds_read_b128 v[172:175], v135 offset:50176
	ds_read_b128 v[176:179], v135 offset:51200
	ds_read_b128 v[180:183], v135 offset:52224
	ds_read_b128 v[184:187], v135 offset:53248
	ds_read_b128 v[224:227], v135 offset:54272
	ds_read_b128 v[228:231], v135 offset:55296
	ds_read_b128 v[232:235], v135 offset:56320
	global_load_lds_dwordx4 v[202:203], off
	v_lshl_add_u64 v[202:203], v[236:237], 0, s[26:27]
	s_mov_b32 m0, s61
	s_nop 0
	global_load_lds_dwordx4 v[202:203], off
	v_lshl_add_u64 v[202:203], s[42:43], 0, v[0:1]
	s_mov_b32 m0, s72
	s_nop 0
	global_load_lds_dwordx4 v[202:203], off
	v_lshl_add_u64 v[202:203], s[42:43], 0, v[130:131]
	s_mov_b32 m0, s69
	s_nop 0
	global_load_lds_dwordx4 v[202:203], off
	v_lshl_add_u64 v[202:203], v[238:239], 0, s[26:27]
	s_mov_b32 m0, s59
	s_nop 0
	global_load_lds_dwordx4 v[202:203], off
	v_lshl_add_u64 v[202:203], v[240:241], 0, s[26:27]
	s_mov_b32 m0, s60
	s_nop 0
	global_load_lds_dwordx4 v[202:203], off
	s_waitcnt vmcnt(8)
	s_waitcnt lgkmcnt(0)
	s_barrier
	s_waitcnt lgkmcnt(0)
	v_mfma_f32_16x16x32_bf16 v[62:65], v[136:139], v[168:171], v[62:65]
	v_mfma_f32_16x16x32_bf16 v[58:61], v[144:147], v[168:171], v[58:61]
	v_mfma_f32_16x16x32_bf16 v[54:57], v[136:139], v[176:179], v[54:57]
	v_mfma_f32_16x16x32_bf16 v[46:49], v[144:147], v[176:179], v[46:49]
	v_mfma_f32_16x16x32_bf16 v[38:41], v[136:139], v[184:187], v[38:41]
	v_mfma_f32_16x16x32_bf16 v[30:33], v[144:147], v[184:187], v[30:33]
	v_mfma_f32_16x16x32_bf16 v[22:25], v[136:139], v[228:231], v[22:25]
	v_mfma_f32_16x16x32_bf16 v[14:17], v[144:147], v[228:231], v[14:17]
	v_mfma_f32_16x16x32_bf16 v[62:65], v[140:143], v[172:175], v[62:65]
	v_mfma_f32_16x16x32_bf16 v[58:61], v[148:151], v[172:175], v[58:61]
	v_mfma_f32_16x16x32_bf16 v[54:57], v[140:143], v[180:183], v[54:57]
	v_mfma_f32_16x16x32_bf16 v[46:49], v[148:151], v[180:183], v[46:49]
	v_mfma_f32_16x16x32_bf16 v[38:41], v[140:143], v[224:227], v[38:41]
	v_mfma_f32_16x16x32_bf16 v[30:33], v[148:151], v[224:227], v[30:33]
	v_mfma_f32_16x16x32_bf16 v[22:25], v[140:143], v[232:235], v[22:25]
	v_mfma_f32_16x16x32_bf16 v[14:17], v[148:151], v[232:235], v[14:17]
	v_mfma_f32_16x16x32_bf16 v[50:53], v[152:155], v[168:171], v[50:53]
	v_mfma_f32_16x16x32_bf16 v[42:45], v[160:163], v[168:171], v[42:45]
	v_mfma_f32_16x16x32_bf16 v[34:37], v[152:155], v[176:179], v[34:37]
	v_mfma_f32_16x16x32_bf16 v[26:29], v[160:163], v[176:179], v[26:29]
	v_mfma_f32_16x16x32_bf16 v[18:21], v[152:155], v[184:187], v[18:21]
	v_mfma_f32_16x16x32_bf16 v[10:13], v[160:163], v[184:187], v[10:13]
	v_mfma_f32_16x16x32_bf16 v[6:9], v[152:155], v[228:231], v[6:9]
	v_mfma_f32_16x16x32_bf16 v[2:5], v[160:163], v[228:231], v[2:5]
	v_mfma_f32_16x16x32_bf16 v[50:53], v[156:159], v[172:175], v[50:53]
	v_mfma_f32_16x16x32_bf16 v[42:45], v[164:167], v[172:175], v[42:45]
	v_mfma_f32_16x16x32_bf16 v[34:37], v[156:159], v[180:183], v[34:37]
	v_mfma_f32_16x16x32_bf16 v[26:29], v[164:167], v[180:183], v[26:29]
	v_mfma_f32_16x16x32_bf16 v[18:21], v[156:159], v[224:227], v[18:21]
	v_mfma_f32_16x16x32_bf16 v[10:13], v[164:167], v[224:227], v[10:13]
	v_mfma_f32_16x16x32_bf16 v[6:9], v[156:159], v[232:235], v[6:9]
	v_mfma_f32_16x16x32_bf16 v[2:5], v[164:167], v[232:235], v[2:5]
	s_barrier
	s_andn2_b64 vcc, exec, s[40:41]
	s_mov_b64 s[42:43], -1
	s_mov_b64 s[40:41], 0
	s_movk_i32 s44, 0x100
	s_cbranch_vccz .LBB0_546
	v_readlane_b32 s4, v254, 17
	s_mul_i32 s5, s2, 0x5d2
	s_lshr_b32 s5, s5, 16
	v_and_b32_e32 v0, 63, v204
	v_lshrrev_b32_e32 v130, 5, v0
	v_and_b32_e32 v131, 31, v0
	s_lshr_b32 vcc_lo, s52, 8
	s_lshl_b32 vcc_lo, vcc_lo, 6
	v_add_u32_e32 v134, vcc_lo, v130
	v_lshlrev_b32_e32 v134, 12, v134
	s_or_b32 vcc_hi, s4, s58
	v_or_b32_e32 v135, vcc_hi, v131
	v_lshl_add_u32 v134, v135, 2, v134
	v_add_u32_e32 v134, 0x8000000, v134
	s_lshr_b32 vcc_lo, s52, 6
	s_mul_i32 vcc_lo, vcc_lo, 0x900
	s_add_u32 vcc_lo, vcc_lo, 0x20200
	v_and_b32_e32 v136, 15, v132
	v_mul_u32_u24_e32 v136, 0x90, v136
	v_lshl_add_u32 v136, v133, 4, v136
	v_add_u32_e32 v136, vcc_lo, v136
	v_mul_u32_u24_e32 v137, 0x90, v130
	v_lshl_add_u32 v137, v131, 2, v137
	v_add_u32_e32 v137, vcc_lo, v137
	s_cmp_lg_u32 s5, 0
	s_cbranch_scc1 .Lg2s_q1
	v_mov_b32_e32 v138, v134
	v_add_u32_e32 v139, 0x2000, v134
	v_add_u32_e32 v140, 0x4000, v134
	v_add_u32_e32 v141, 0x6000, v134
	v_add_u32_e32 v142, 0x8000, v134
	v_add_u32_e32 v143, 0xa000, v134
	v_add_u32_e32 v144, 0xc000, v134
	v_add_u32_e32 v145, 0xe000, v134
	v_pk_mul_f32 v[126:127], v[126:127], 0.5 op_sel_hi:[1,0]
	v_pk_mul_f32 v[128:129], v[128:129], 0.5 op_sel_hi:[1,0]
	v_pk_mul_f32 v[122:123], v[122:123], 0.5 op_sel_hi:[1,0]
	v_pk_mul_f32 v[124:125], v[124:125], 0.5 op_sel_hi:[1,0]
	ds_write_b128 v136, v[126:129]
	ds_write_b128 v136, v[122:125] offset:64
	ds_read_b32 v146, v137
	ds_read_b32 v147, v137 offset:288
	ds_read_b32 v148, v137 offset:576
	ds_read_b32 v149, v137 offset:864
	ds_read_b32 v150, v137 offset:1152
	ds_read_b32 v151, v137 offset:1440
	ds_read_b32 v152, v137 offset:1728
	ds_read_b32 v153, v137 offset:2016
	s_waitcnt lgkmcnt(0)
	global_atomic_add_f32 v138, v146, s[24:25]
	global_atomic_add_f32 v139, v147, s[24:25]
	global_atomic_add_f32 v140, v148, s[24:25]
	global_atomic_add_f32 v141, v149, s[24:25]
	global_atomic_add_f32 v142, v150, s[24:25]
	global_atomic_add_f32 v143, v151, s[24:25]
	global_atomic_add_f32 v144, v152, s[24:25]
	global_atomic_add_f32 v145, v153, s[24:25]
	v_pk_mul_f32 v[114:115], v[114:115], 0.5 op_sel_hi:[1,0]
	v_pk_mul_f32 v[116:117], v[116:117], 0.5 op_sel_hi:[1,0]
	v_pk_mul_f32 v[106:107], v[106:107], 0.5 op_sel_hi:[1,0]
	v_pk_mul_f32 v[108:109], v[108:109], 0.5 op_sel_hi:[1,0]
	ds_write_b128 v136, v[114:117]
	ds_write_b128 v136, v[106:109] offset:64
	ds_read_b32 v154, v137
	ds_read_b32 v155, v137 offset:288
	ds_read_b32 v156, v137 offset:576
	ds_read_b32 v157, v137 offset:864
	ds_read_b32 v158, v137 offset:1152
	ds_read_b32 v159, v137 offset:1440
	ds_read_b32 v160, v137 offset:1728
	ds_read_b32 v161, v137 offset:2016
	s_waitcnt lgkmcnt(0)
	global_atomic_add_f32 v138, v154, s[24:25] offset:512
	global_atomic_add_f32 v139, v155, s[24:25] offset:512
	global_atomic_add_f32 v140, v156, s[24:25] offset:512
	global_atomic_add_f32 v141, v157, s[24:25] offset:512
	global_atomic_add_f32 v142, v158, s[24:25] offset:512
	global_atomic_add_f32 v143, v159, s[24:25] offset:512
	global_atomic_add_f32 v144, v160, s[24:25] offset:512
	global_atomic_add_f32 v145, v161, s[24:25] offset:512
	v_add_u32_e32 v138, 0x10000, v134
	v_add_u32_e32 v139, 0x12000, v134
	v_add_u32_e32 v140, 0x14000, v134
	v_add_u32_e32 v141, 0x16000, v134
	v_add_u32_e32 v142, 0x18000, v134
	v_add_u32_e32 v143, 0x1a000, v134
	v_add_u32_e32 v144, 0x1c000, v134
	v_add_u32_e32 v145, 0x1e000, v134
	v_pk_mul_f32 v[118:119], v[118:119], 0.5 op_sel_hi:[1,0]
	v_pk_mul_f32 v[120:121], v[120:121], 0.5 op_sel_hi:[1,0]
	v_pk_mul_f32 v[110:111], v[110:111], 0.5 op_sel_hi:[1,0]
	v_pk_mul_f32 v[112:113], v[112:113], 0.5 op_sel_hi:[1,0]
	ds_write_b128 v136, v[118:121]
	ds_write_b128 v136, v[110:113] offset:64
	ds_read_b32 v146, v137
	ds_read_b32 v147, v137 offset:288
	ds_read_b32 v148, v137 offset:576
	ds_read_b32 v149, v137 offset:864
	ds_read_b32 v150, v137 offset:1152
	ds_read_b32 v151, v137 offset:1440
	ds_read_b32 v152, v137 offset:1728
	ds_read_b32 v153, v137 offset:2016
	s_waitcnt lgkmcnt(0)
	global_atomic_add_f32 v138, v146, s[24:25]
	global_atomic_add_f32 v139, v147, s[24:25]
	global_atomic_add_f32 v140, v148, s[24:25]
	global_atomic_add_f32 v141, v149, s[24:25]
	global_atomic_add_f32 v142, v150, s[24:25]
	global_atomic_add_f32 v143, v151, s[24:25]
	global_atomic_add_f32 v144, v152, s[24:25]
	global_atomic_add_f32 v145, v153, s[24:25]
	v_pk_mul_f32 v[98:99], v[98:99], 0.5 op_sel_hi:[1,0]
	v_pk_mul_f32 v[100:101], v[100:101], 0.5 op_sel_hi:[1,0]
	v_pk_mul_f32 v[90:91], v[90:91], 0.5 op_sel_hi:[1,0]
	v_pk_mul_f32 v[92:93], v[92:93], 0.5 op_sel_hi:[1,0]
	ds_write_b128 v136, v[98:101]
	ds_write_b128 v136, v[90:93] offset:64
	ds_read_b32 v154, v137
	ds_read_b32 v155, v137 offset:288
	ds_read_b32 v156, v137 offset:576
	ds_read_b32 v157, v137 offset:864
	ds_read_b32 v158, v137 offset:1152
	ds_read_b32 v159, v137 offset:1440
	ds_read_b32 v160, v137 offset:1728
	ds_read_b32 v161, v137 offset:2016
	s_waitcnt lgkmcnt(0)
	global_atomic_add_f32 v138, v154, s[24:25] offset:512
	global_atomic_add_f32 v139, v155, s[24:25] offset:512
	global_atomic_add_f32 v140, v156, s[24:25] offset:512
	global_atomic_add_f32 v141, v157, s[24:25] offset:512
	global_atomic_add_f32 v142, v158, s[24:25] offset:512
	global_atomic_add_f32 v143, v159, s[24:25] offset:512
	global_atomic_add_f32 v144, v160, s[24:25] offset:512
	global_atomic_add_f32 v145, v161, s[24:25] offset:512

.LBB0_737:
	s_add_u32 s8, s40, 0xfffc0080
	s_addc_u32 s9, s41, -1
	s_add_i32 s10, 0, 0x10000
	s_cmp_eq_u32 s59, 12
	s_cselect_b32 s45, s0, s9
	s_cselect_b32 s44, s1, s8
	v_add_u32_e32 v0, s10, v164
	s_cselect_b32 s43, s5, s58
	s_cselect_b32 s42, s25, s28
	s_add_i32 s11, 0, 0x14000
	ds_read_b128 v[130:133], v0
	ds_read_b128 v[150:153], v0 offset:1024
	ds_read_b128 v[154:157], v0 offset:2048
	ds_read_b128 v[158:161], v0 offset:3072
	v_add_u32_e32 v0, s11, v164
	ds_read_b128 v[166:169], v0
	ds_read_b128 v[170:173], v0 offset:1024
	ds_read_b128 v[174:177], v0 offset:2048
	ds_read_b128 v[178:181], v0 offset:3072
	v_lshl_add_u64 v[134:135], s[40:41], 0, v[146:147]
	s_add_i32 m0, s73, 0xc000
	ds_read_b128 v[182:185], v165
	ds_read_b128 v[224:227], v165 offset:1024
	ds_read_b128 v[228:231], v165 offset:2048
	ds_read_b128 v[232:235], v165 offset:3072
	ds_read_b128 v[236:239], v165 offset:4096
	ds_read_b128 v[240:243], v165 offset:5120
	ds_read_b128 v[244:247], v165 offset:6144
	ds_read_b128 v[248:251], v165 offset:7168
	global_load_lds_dwordx4 v[134:135], off
	v_lshl_add_u64 v[134:135], s[40:41], 0, v[148:149]
	s_add_i32 m0, s73, 0xe000
	s_nop 0
	global_load_lds_dwordx4 v[134:135], off
	s_waitcnt vmcnt(8)
	s_waitcnt lgkmcnt(0)
	s_barrier
	s_waitcnt lgkmcnt(0)
	v_mfma_f32_16x16x32_bf16 v[126:129], v[130:133], v[182:185], v[126:129]
	v_mfma_f32_16x16x32_bf16 v[122:125], v[154:157], v[182:185], v[122:125]
	v_mfma_f32_16x16x32_bf16 v[118:121], v[130:133], v[228:231], v[118:121]
	v_mfma_f32_16x16x32_bf16 v[114:117], v[154:157], v[228:231], v[114:117]
	v_mfma_f32_16x16x32_bf16 v[106:109], v[130:133], v[236:239], v[106:109]
	v_mfma_f32_16x16x32_bf16 v[98:101], v[154:157], v[236:239], v[98:101]
	v_mfma_f32_16x16x32_bf16 v[90:93], v[130:133], v[244:247], v[90:93]
	v_mfma_f32_16x16x32_bf16 v[82:85], v[154:157], v[244:247], v[82:85]
	v_mfma_f32_16x16x32_bf16 v[126:129], v[150:153], v[224:227], v[126:129]
	v_mfma_f32_16x16x32_bf16 v[122:125], v[158:161], v[224:227], v[122:125]
	v_mfma_f32_16x16x32_bf16 v[118:121], v[150:153], v[232:235], v[118:121]
	v_mfma_f32_16x16x32_bf16 v[114:117], v[158:161], v[232:235], v[114:117]
	v_mfma_f32_16x16x32_bf16 v[106:109], v[150:153], v[240:243], v[106:109]
	v_mfma_f32_16x16x32_bf16 v[98:101], v[158:161], v[240:243], v[98:101]
	v_mfma_f32_16x16x32_bf16 v[90:93], v[150:153], v[248:251], v[90:93]
	v_mfma_f32_16x16x32_bf16 v[82:85], v[158:161], v[248:251], v[82:85]
	v_mfma_f32_16x16x32_bf16 v[110:113], v[166:169], v[182:185], v[110:113]
	v_mfma_f32_16x16x32_bf16 v[102:105], v[174:177], v[182:185], v[102:105]
	v_mfma_f32_16x16x32_bf16 v[94:97], v[166:169], v[228:231], v[94:97]
	v_mfma_f32_16x16x32_bf16 v[86:89], v[174:177], v[228:231], v[86:89]
	v_mfma_f32_16x16x32_bf16 v[78:81], v[166:169], v[236:239], v[78:81]
	v_mfma_f32_16x16x32_bf16 v[74:77], v[174:177], v[236:239], v[74:77]
	v_mfma_f32_16x16x32_bf16 v[70:73], v[166:169], v[244:247], v[70:73]
	v_mfma_f32_16x16x32_bf16 v[66:69], v[174:177], v[244:247], v[66:69]
	v_mfma_f32_16x16x32_bf16 v[110:113], v[170:173], v[224:227], v[110:113]
	v_mfma_f32_16x16x32_bf16 v[102:105], v[178:181], v[224:227], v[102:105]
	v_mfma_f32_16x16x32_bf16 v[94:97], v[170:173], v[232:235], v[94:97]
	v_mfma_f32_16x16x32_bf16 v[86:89], v[178:181], v[232:235], v[86:89]
	v_mfma_f32_16x16x32_bf16 v[78:81], v[170:173], v[240:243], v[78:81]
	v_mfma_f32_16x16x32_bf16 v[74:77], v[178:181], v[240:243], v[74:77]
	v_mfma_f32_16x16x32_bf16 v[70:73], v[170:173], v[248:251], v[70:73]
	v_mfma_f32_16x16x32_bf16 v[66:69], v[178:181], v[248:251], v[66:69]
	s_barrier
	s_add_i32 s8, s10, s94
	v_lshl_add_u64 v[134:135], s[42:43], 0, v[138:139]
	s_mov_b32 m0, s8
	ds_read_b128 v[182:185], v165 offset:16384
	ds_read_b128 v[224:227], v165 offset:17408
	ds_read_b128 v[228:231], v165 offset:18432
	ds_read_b128 v[232:235], v165 offset:19456
	ds_read_b128 v[236:239], v165 offset:20480
	ds_read_b128 v[240:243], v165 offset:21504
	ds_read_b128 v[244:247], v165 offset:22528
	ds_read_b128 v[248:251], v165 offset:23552
	global_load_lds_dwordx4 v[134:135], off
	s_add_i32 m0, s8, 0x2000
	s_add_u32 s8, s42, 0x40000
	v_lshl_add_u64 v[162:163], s[42:43], 0, v[142:143]
	s_addc_u32 s9, s43, 0
	s_add_i32 s10, s11, s94
	global_load_lds_dwordx4 v[162:163], off
	v_lshl_add_u64 v[186:187], s[8:9], 0, v[138:139]
	s_mov_b32 m0, s10
	v_lshl_add_u64 v[202:203], s[44:45], 0, v[140:141]
	global_load_lds_dwordx4 v[186:187], off
	v_lshl_add_u64 v[186:187], s[8:9], 0, v[142:143]
	s_add_i32 m0, s10, 0x2000
	s_nop 0
	global_load_lds_dwordx4 v[186:187], off
	v_lshl_add_u64 v[186:187], s[44:45], 0, v[136:137]
	s_mov_b32 m0, s73
	s_nop 0
	global_load_lds_dwordx4 v[186:187], off
	s_mov_b32 m0, s95
	s_nop 0
	global_load_lds_dwordx4 v[202:203], off
	s_waitcnt vmcnt(8)
	s_waitcnt lgkmcnt(0)
	s_barrier
	s_waitcnt lgkmcnt(0)
	v_mfma_f32_16x16x32_bf16 v[62:65], v[130:133], v[182:185], v[62:65]
	v_mfma_f32_16x16x32_bf16 v[58:61], v[154:157], v[182:185], v[58:61]
	v_mfma_f32_16x16x32_bf16 v[54:57], v[130:133], v[228:231], v[54:57]
	v_mfma_f32_16x16x32_bf16 v[50:53], v[154:157], v[228:231], v[50:53]
	v_mfma_f32_16x16x32_bf16 v[42:45], v[130:133], v[236:239], v[42:45]
	v_mfma_f32_16x16x32_bf16 v[34:37], v[154:157], v[236:239], v[34:37]
	v_mfma_f32_16x16x32_bf16 v[26:29], v[130:133], v[244:247], v[26:29]
	v_mfma_f32_16x16x32_bf16 v[18:21], v[154:157], v[244:247], v[18:21]
	v_mfma_f32_16x16x32_bf16 v[62:65], v[150:153], v[224:227], v[62:65]
	v_mfma_f32_16x16x32_bf16 v[58:61], v[158:161], v[224:227], v[58:61]
	v_mfma_f32_16x16x32_bf16 v[54:57], v[150:153], v[232:235], v[54:57]
	v_mfma_f32_16x16x32_bf16 v[50:53], v[158:161], v[232:235], v[50:53]
	v_mfma_f32_16x16x32_bf16 v[42:45], v[150:153], v[240:243], v[42:45]
	v_mfma_f32_16x16x32_bf16 v[34:37], v[158:161], v[240:243], v[34:37]
	v_mfma_f32_16x16x32_bf16 v[26:29], v[150:153], v[248:251], v[26:29]
	v_mfma_f32_16x16x32_bf16 v[18:21], v[158:161], v[248:251], v[18:21]
	v_mfma_f32_16x16x32_bf16 v[46:49], v[166:169], v[182:185], v[46:49]
	v_mfma_f32_16x16x32_bf16 v[38:41], v[174:177], v[182:185], v[38:41]
	v_mfma_f32_16x16x32_bf16 v[30:33], v[166:169], v[228:231], v[30:33]
	v_mfma_f32_16x16x32_bf16 v[22:25], v[174:177], v[228:231], v[22:25]
	v_mfma_f32_16x16x32_bf16 v[14:17], v[166:169], v[236:239], v[14:17]
	v_mfma_f32_16x16x32_bf16 v[10:13], v[174:177], v[236:239], v[10:13]
	v_mfma_f32_16x16x32_bf16 v[6:9], v[166:169], v[244:247], v[6:9]
	v_mfma_f32_16x16x32_bf16 v[2:5], v[174:177], v[244:247], v[2:5]
	v_mfma_f32_16x16x32_bf16 v[46:49], v[170:173], v[224:227], v[46:49]
	v_mfma_f32_16x16x32_bf16 v[38:41], v[178:181], v[224:227], v[38:41]
	v_mfma_f32_16x16x32_bf16 v[30:33], v[170:173], v[232:235], v[30:33]
	v_mfma_f32_16x16x32_bf16 v[22:25], v[178:181], v[232:235], v[22:25]
	v_mfma_f32_16x16x32_bf16 v[14:17], v[170:173], v[240:243], v[14:17]
	v_mfma_f32_16x16x32_bf16 v[10:13], v[178:181], v[240:243], v[10:13]
	v_mfma_f32_16x16x32_bf16 v[6:9], v[170:173], v[248:251], v[6:9]
	v_mfma_f32_16x16x32_bf16 v[2:5], v[178:181], v[248:251], v[2:5]
	s_barrier
	s_add_i32 s10, 0, 0x18000
	v_add_u32_e32 v0, s10, v164
	s_add_i32 s11, 0, 0x1c000
	ds_read_b128 v[130:133], v0
	ds_read_b128 v[150:153], v0 offset:1024
	ds_read_b128 v[154:157], v0 offset:2048
	ds_read_b128 v[158:161], v0 offset:3072
	v_add_u32_e32 v0, s11, v164
	ds_read_b128 v[166:169], v0
	ds_read_b128 v[170:173], v0 offset:1024
	ds_read_b128 v[174:177], v0 offset:2048
	ds_read_b128 v[178:181], v0 offset:3072
	s_add_u32 s8, s44, 0x40000
	s_addc_u32 s9, s45, 0
	s_mov_b32 m0, s96
	v_lshl_add_u64 v[208:209], s[8:9], 0, v[136:137]
	ds_read_b128 v[182:185], v165 offset:32768
	ds_read_b128 v[224:227], v165 offset:33792
	ds_read_b128 v[228:231], v165 offset:34816
	ds_read_b128 v[232:235], v165 offset:35840
	ds_read_b128 v[236:239], v165 offset:36864
	ds_read_b128 v[240:243], v165 offset:37888
	ds_read_b128 v[244:247], v165 offset:38912
	ds_read_b128 v[248:251], v165 offset:39936
	global_load_lds_dwordx4 v[208:209], off
	v_lshl_add_u64 v[208:209], s[8:9], 0, v[140:141]
	s_mov_b32 m0, s97
	s_nop 0
	global_load_lds_dwordx4 v[208:209], off
	s_waitcnt vmcnt(8)
	s_waitcnt lgkmcnt(0)
	s_barrier
	s_waitcnt lgkmcnt(0)
	v_mfma_f32_16x16x32_bf16 v[126:129], v[130:133], v[182:185], v[126:129]
	v_mfma_f32_16x16x32_bf16 v[122:125], v[154:157], v[182:185], v[122:125]
	v_mfma_f32_16x16x32_bf16 v[118:121], v[130:133], v[228:231], v[118:121]
	v_mfma_f32_16x16x32_bf16 v[114:117], v[154:157], v[228:231], v[114:117]
	v_mfma_f32_16x16x32_bf16 v[106:109], v[130:133], v[236:239], v[106:109]
	v_mfma_f32_16x16x32_bf16 v[98:101], v[154:157], v[236:239], v[98:101]
	v_mfma_f32_16x16x32_bf16 v[90:93], v[130:133], v[244:247], v[90:93]
	v_mfma_f32_16x16x32_bf16 v[82:85], v[154:157], v[244:247], v[82:85]
	v_mfma_f32_16x16x32_bf16 v[126:129], v[150:153], v[224:227], v[126:129]
	v_mfma_f32_16x16x32_bf16 v[122:125], v[158:161], v[224:227], v[122:125]
	v_mfma_f32_16x16x32_bf16 v[118:121], v[150:153], v[232:235], v[118:121]
	v_mfma_f32_16x16x32_bf16 v[114:117], v[158:161], v[232:235], v[114:117]
	v_mfma_f32_16x16x32_bf16 v[106:109], v[150:153], v[240:243], v[106:109]
	v_mfma_f32_16x16x32_bf16 v[98:101], v[158:161], v[240:243], v[98:101]
	v_mfma_f32_16x16x32_bf16 v[90:93], v[150:153], v[248:251], v[90:93]
	v_mfma_f32_16x16x32_bf16 v[82:85], v[158:161], v[248:251], v[82:85]
	v_mfma_f32_16x16x32_bf16 v[110:113], v[166:169], v[182:185], v[110:113]
	v_mfma_f32_16x16x32_bf16 v[102:105], v[174:177], v[182:185], v[102:105]
	v_mfma_f32_16x16x32_bf16 v[94:97], v[166:169], v[228:231], v[94:97]
	v_mfma_f32_16x16x32_bf16 v[86:89], v[174:177], v[228:231], v[86:89]
	v_mfma_f32_16x16x32_bf16 v[78:81], v[166:169], v[236:239], v[78:81]
	v_mfma_f32_16x16x32_bf16 v[74:77], v[174:177], v[236:239], v[74:77]
	v_mfma_f32_16x16x32_bf16 v[70:73], v[166:169], v[244:247], v[70:73]
	v_mfma_f32_16x16x32_bf16 v[66:69], v[174:177], v[244:247], v[66:69]
	v_mfma_f32_16x16x32_bf16 v[110:113], v[170:173], v[224:227], v[110:113]
	v_mfma_f32_16x16x32_bf16 v[102:105], v[178:181], v[224:227], v[102:105]
	v_mfma_f32_16x16x32_bf16 v[94:97], v[170:173], v[232:235], v[94:97]
	v_mfma_f32_16x16x32_bf16 v[86:89], v[178:181], v[232:235], v[86:89]
	v_mfma_f32_16x16x32_bf16 v[78:81], v[170:173], v[240:243], v[78:81]
	v_mfma_f32_16x16x32_bf16 v[74:77], v[178:181], v[240:243], v[74:77]
	v_mfma_f32_16x16x32_bf16 v[70:73], v[170:173], v[248:251], v[70:73]
	v_mfma_f32_16x16x32_bf16 v[66:69], v[178:181], v[248:251], v[66:69]
	s_barrier
	s_add_i32 s8, s10, s94
	v_lshl_add_u64 v[134:135], v[134:135], 0, s[26:27]
	s_mov_b32 m0, s8
	ds_read_b128 v[182:185], v165 offset:49152
	ds_read_b128 v[224:227], v165 offset:50176
	ds_read_b128 v[228:231], v165 offset:51200
	ds_read_b128 v[232:235], v165 offset:52224
	ds_read_b128 v[236:239], v165 offset:53248
	ds_read_b128 v[240:243], v165 offset:54272
	ds_read_b128 v[244:247], v165 offset:55296
	ds_read_b128 v[248:251], v165 offset:56320
	global_load_lds_dwordx4 v[134:135], off
	s_add_i32 m0, s8, 0x2000
	s_add_u32 s8, s42, 0x40080
	v_lshl_add_u64 v[134:135], v[162:163], 0, s[26:27]
	s_addc_u32 s9, s43, 0
	s_add_i32 s10, s11, s94
	global_load_lds_dwordx4 v[134:135], off
	v_lshl_add_u64 v[134:135], s[8:9], 0, v[138:139]
	s_mov_b32 m0, s10
	s_nop 0
	global_load_lds_dwordx4 v[134:135], off
	v_lshl_add_u64 v[134:135], s[8:9], 0, v[142:143]
	s_add_i32 m0, s10, 0x2000
	s_nop 0
	global_load_lds_dwordx4 v[134:135], off
	v_lshl_add_u64 v[134:135], v[186:187], 0, s[26:27]
	s_mov_b32 m0, s52
	s_nop 0
	global_load_lds_dwordx4 v[134:135], off
	v_lshl_add_u64 v[134:135], v[202:203], 0, s[26:27]
	s_mov_b32 m0, s53
	s_nop 0
	global_load_lds_dwordx4 v[134:135], off
	s_waitcnt vmcnt(8)
	s_waitcnt lgkmcnt(0)
	s_barrier
	s_waitcnt lgkmcnt(0)
	v_mfma_f32_16x16x32_bf16 v[62:65], v[130:133], v[182:185], v[62:65]
	v_mfma_f32_16x16x32_bf16 v[58:61], v[154:157], v[182:185], v[58:61]
	v_mfma_f32_16x16x32_bf16 v[54:57], v[130:133], v[228:231], v[54:57]
	v_mfma_f32_16x16x32_bf16 v[50:53], v[154:157], v[228:231], v[50:53]
	v_mfma_f32_16x16x32_bf16 v[42:45], v[130:133], v[236:239], v[42:45]
	v_mfma_f32_16x16x32_bf16 v[34:37], v[154:157], v[236:239], v[34:37]
	v_mfma_f32_16x16x32_bf16 v[26:29], v[130:133], v[244:247], v[26:29]
	v_mfma_f32_16x16x32_bf16 v[18:21], v[154:157], v[244:247], v[18:21]
	v_mfma_f32_16x16x32_bf16 v[62:65], v[150:153], v[224:227], v[62:65]
	v_mfma_f32_16x16x32_bf16 v[58:61], v[158:161], v[224:227], v[58:61]
	v_mfma_f32_16x16x32_bf16 v[54:57], v[150:153], v[232:235], v[54:57]
	v_mfma_f32_16x16x32_bf16 v[50:53], v[158:161], v[232:235], v[50:53]
	v_mfma_f32_16x16x32_bf16 v[42:45], v[150:153], v[240:243], v[42:45]
	v_mfma_f32_16x16x32_bf16 v[34:37], v[158:161], v[240:243], v[34:37]
	v_mfma_f32_16x16x32_bf16 v[26:29], v[150:153], v[248:251], v[26:29]
	v_mfma_f32_16x16x32_bf16 v[18:21], v[158:161], v[248:251], v[18:21]
	v_mfma_f32_16x16x32_bf16 v[46:49], v[166:169], v[182:185], v[46:49]
	v_mfma_f32_16x16x32_bf16 v[38:41], v[174:177], v[182:185], v[38:41]
	v_mfma_f32_16x16x32_bf16 v[30:33], v[166:169], v[228:231], v[30:33]
	v_mfma_f32_16x16x32_bf16 v[22:25], v[174:177], v[228:231], v[22:25]
	v_mfma_f32_16x16x32_bf16 v[14:17], v[166:169], v[236:239], v[14:17]
	v_mfma_f32_16x16x32_bf16 v[10:13], v[174:177], v[236:239], v[10:13]
	v_mfma_f32_16x16x32_bf16 v[6:9], v[166:169], v[244:247], v[6:9]
	v_mfma_f32_16x16x32_bf16 v[2:5], v[174:177], v[244:247], v[2:5]
	v_mfma_f32_16x16x32_bf16 v[46:49], v[170:173], v[224:227], v[46:49]
	v_mfma_f32_16x16x32_bf16 v[38:41], v[178:181], v[224:227], v[38:41]
	v_mfma_f32_16x16x32_bf16 v[30:33], v[170:173], v[232:235], v[30:33]
	v_mfma_f32_16x16x32_bf16 v[22:25], v[178:181], v[232:235], v[22:25]
	v_mfma_f32_16x16x32_bf16 v[14:17], v[170:173], v[240:243], v[14:17]
	v_mfma_f32_16x16x32_bf16 v[10:13], v[178:181], v[240:243], v[10:13]
	v_mfma_f32_16x16x32_bf16 v[6:9], v[170:173], v[248:251], v[6:9]
	v_mfma_f32_16x16x32_bf16 v[2:5], v[178:181], v[248:251], v[2:5]
	s_barrier
	s_add_i32 s59, s59, 2
	s_add_u32 s40, s40, 0x100
	s_addc_u32 s41, s41, 0
	s_add_u32 s28, s28, 0x100
	s_addc_u32 s58, s58, 0
	s_cmp_gt_u32 s59, 13
	s_cbranch_scc0 .LBB0_737
	s_and_b64 vcc, exec, s[56:57]
	s_cbranch_vccz .LBB0_740
	s_barrier

.LBB0_1538:
	s_add_u32 s8, s52, 0xfffc0080
	s_addc_u32 s9, s53, -1
	s_add_i32 s10, 0, 0x10000
	s_cmp_eq_u32 s73, 12
	s_cselect_b32 s57, s47, s9
	s_cselect_b32 s56, s67, s8
	v_add_u32_e32 v140, s10, v143
	s_cselect_b32 s55, s45, s72
	s_cselect_b32 s54, s68, s69
	s_add_i32 s11, 0, 0x14000
	ds_read_b128 v[146:149], v140
	ds_read_b128 v[150:153], v140 offset:1024
	ds_read_b128 v[154:157], v140 offset:2048
	ds_read_b128 v[158:161], v140 offset:3072
	v_add_u32_e32 v140, s11, v143
	ds_read_b128 v[162:165], v140
	ds_read_b128 v[166:169], v140 offset:1024
	ds_read_b128 v[170:173], v140 offset:2048
	ds_read_b128 v[174:177], v140 offset:3072
	v_lshl_add_u64 v[140:141], s[52:53], 0, v[136:137]
	s_add_i32 m0, s58, 0xc000
	ds_read_b128 v[178:181], v145
	ds_read_b128 v[182:185], v145 offset:1024
	ds_read_b128 v[224:227], v145 offset:2048
	ds_read_b128 v[228:231], v145 offset:3072
	ds_read_b128 v[232:235], v145 offset:4096
	ds_read_b128 v[236:239], v145 offset:5120
	ds_read_b128 v[240:243], v145 offset:6144
	ds_read_b128 v[244:247], v145 offset:7168
	global_load_lds_dwordx4 v[140:141], off
	v_lshl_add_u64 v[140:141], s[52:53], 0, v[138:139]
	s_add_i32 m0, s58, 0xe000
	s_nop 0
	global_load_lds_dwordx4 v[140:141], off
	s_waitcnt vmcnt(8)
	s_waitcnt lgkmcnt(0)
	s_barrier
	s_waitcnt lgkmcnt(0)
	v_mfma_f32_16x16x32_bf16 v[126:129], v[146:149], v[178:181], v[126:129]
	v_mfma_f32_16x16x32_bf16 v[122:125], v[154:157], v[178:181], v[122:125]
	v_mfma_f32_16x16x32_bf16 v[110:113], v[146:149], v[224:227], v[110:113]
	v_mfma_f32_16x16x32_bf16 v[106:109], v[154:157], v[224:227], v[106:109]
	v_mfma_f32_16x16x32_bf16 v[102:105], v[146:149], v[232:235], v[102:105]
	v_mfma_f32_16x16x32_bf16 v[98:101], v[154:157], v[232:235], v[98:101]
	v_mfma_f32_16x16x32_bf16 v[78:81], v[146:149], v[240:243], v[78:81]
	v_mfma_f32_16x16x32_bf16 v[74:77], v[154:157], v[240:243], v[74:77]
	v_mfma_f32_16x16x32_bf16 v[126:129], v[150:153], v[182:185], v[126:129]
	v_mfma_f32_16x16x32_bf16 v[122:125], v[158:161], v[182:185], v[122:125]
	v_mfma_f32_16x16x32_bf16 v[110:113], v[150:153], v[228:231], v[110:113]
	v_mfma_f32_16x16x32_bf16 v[106:109], v[158:161], v[228:231], v[106:109]
	v_mfma_f32_16x16x32_bf16 v[102:105], v[150:153], v[236:239], v[102:105]
	v_mfma_f32_16x16x32_bf16 v[98:101], v[158:161], v[236:239], v[98:101]
	v_mfma_f32_16x16x32_bf16 v[78:81], v[150:153], v[244:247], v[78:81]
	v_mfma_f32_16x16x32_bf16 v[74:77], v[158:161], v[244:247], v[74:77]
	v_mfma_f32_16x16x32_bf16 v[118:121], v[162:165], v[178:181], v[118:121]
	v_mfma_f32_16x16x32_bf16 v[114:117], v[170:173], v[178:181], v[114:117]
	v_mfma_f32_16x16x32_bf16 v[94:97], v[162:165], v[224:227], v[94:97]
	v_mfma_f32_16x16x32_bf16 v[90:93], v[170:173], v[224:227], v[90:93]
	v_mfma_f32_16x16x32_bf16 v[86:89], v[162:165], v[232:235], v[86:89]
	v_mfma_f32_16x16x32_bf16 v[82:85], v[170:173], v[232:235], v[82:85]
	v_mfma_f32_16x16x32_bf16 v[70:73], v[162:165], v[240:243], v[70:73]
	v_mfma_f32_16x16x32_bf16 v[66:69], v[170:173], v[240:243], v[66:69]
	v_mfma_f32_16x16x32_bf16 v[118:121], v[166:169], v[182:185], v[118:121]
	v_mfma_f32_16x16x32_bf16 v[114:117], v[174:177], v[182:185], v[114:117]
	v_mfma_f32_16x16x32_bf16 v[94:97], v[166:169], v[228:231], v[94:97]
	v_mfma_f32_16x16x32_bf16 v[90:93], v[174:177], v[228:231], v[90:93]
	v_mfma_f32_16x16x32_bf16 v[86:89], v[166:169], v[236:239], v[86:89]
	v_mfma_f32_16x16x32_bf16 v[82:85], v[174:177], v[236:239], v[82:85]
	v_mfma_f32_16x16x32_bf16 v[70:73], v[166:169], v[244:247], v[70:73]
	v_mfma_f32_16x16x32_bf16 v[66:69], v[174:177], v[244:247], v[66:69]
	s_barrier
	s_add_i32 s8, s10, s28
	v_lshl_add_u64 v[140:141], s[54:55], 0, v[0:1]
	s_mov_b32 m0, s8
	ds_read_b128 v[178:181], v145 offset:16384
	ds_read_b128 v[182:185], v145 offset:17408
	ds_read_b128 v[224:227], v145 offset:18432
	ds_read_b128 v[228:231], v145 offset:19456
	ds_read_b128 v[232:235], v145 offset:20480
	ds_read_b128 v[236:239], v145 offset:21504
	ds_read_b128 v[240:243], v145 offset:22528
	ds_read_b128 v[244:247], v145 offset:23552
	global_load_lds_dwordx4 v[140:141], off
	s_add_i32 m0, s8, 0x2000
	s_add_u32 s8, s54, 0x40000
	v_lshl_add_u64 v[186:187], s[54:55], 0, v[130:131]
	s_addc_u32 s9, s55, 0
	s_add_i32 s10, s11, s28
	global_load_lds_dwordx4 v[186:187], off
	v_lshl_add_u64 v[202:203], s[8:9], 0, v[0:1]
	s_mov_b32 m0, s10
	v_lshl_add_u64 v[208:209], s[56:57], 0, v[132:133]
	global_load_lds_dwordx4 v[202:203], off
	v_lshl_add_u64 v[202:203], s[8:9], 0, v[130:131]
	s_add_i32 m0, s10, 0x2000
	s_nop 0
	global_load_lds_dwordx4 v[202:203], off
	v_lshl_add_u64 v[202:203], s[56:57], 0, v[134:135]
	s_mov_b32 m0, s58
	s_nop 0
	global_load_lds_dwordx4 v[202:203], off
	s_mov_b32 m0, s59
	s_nop 0
	global_load_lds_dwordx4 v[208:209], off
	s_waitcnt vmcnt(8)
	s_waitcnt lgkmcnt(0)
	s_barrier
	s_waitcnt lgkmcnt(0)
	v_mfma_f32_16x16x32_bf16 v[62:65], v[146:149], v[178:181], v[62:65]
	v_mfma_f32_16x16x32_bf16 v[58:61], v[154:157], v[178:181], v[58:61]
	v_mfma_f32_16x16x32_bf16 v[46:49], v[146:149], v[224:227], v[46:49]
	v_mfma_f32_16x16x32_bf16 v[42:45], v[154:157], v[224:227], v[42:45]
	v_mfma_f32_16x16x32_bf16 v[30:33], v[146:149], v[232:235], v[30:33]
	v_mfma_f32_16x16x32_bf16 v[26:29], v[154:157], v[232:235], v[26:29]
	v_mfma_f32_16x16x32_bf16 v[14:17], v[146:149], v[240:243], v[14:17]
	v_mfma_f32_16x16x32_bf16 v[10:13], v[154:157], v[240:243], v[10:13]
	v_mfma_f32_16x16x32_bf16 v[62:65], v[150:153], v[182:185], v[62:65]
	v_mfma_f32_16x16x32_bf16 v[58:61], v[158:161], v[182:185], v[58:61]
	v_mfma_f32_16x16x32_bf16 v[46:49], v[150:153], v[228:231], v[46:49]
	v_mfma_f32_16x16x32_bf16 v[42:45], v[158:161], v[228:231], v[42:45]
	v_mfma_f32_16x16x32_bf16 v[30:33], v[150:153], v[236:239], v[30:33]
	v_mfma_f32_16x16x32_bf16 v[26:29], v[158:161], v[236:239], v[26:29]
	v_mfma_f32_16x16x32_bf16 v[14:17], v[150:153], v[244:247], v[14:17]
	v_mfma_f32_16x16x32_bf16 v[10:13], v[158:161], v[244:247], v[10:13]
	v_mfma_f32_16x16x32_bf16 v[54:57], v[162:165], v[178:181], v[54:57]
	v_mfma_f32_16x16x32_bf16 v[50:53], v[170:173], v[178:181], v[50:53]
	v_mfma_f32_16x16x32_bf16 v[38:41], v[162:165], v[224:227], v[38:41]
	v_mfma_f32_16x16x32_bf16 v[34:37], v[170:173], v[224:227], v[34:37]
	v_mfma_f32_16x16x32_bf16 v[22:25], v[162:165], v[232:235], v[22:25]
	v_mfma_f32_16x16x32_bf16 v[18:21], v[170:173], v[232:235], v[18:21]
	v_mfma_f32_16x16x32_bf16 v[6:9], v[162:165], v[240:243], v[6:9]
	v_mfma_f32_16x16x32_bf16 v[2:5], v[170:173], v[240:243], v[2:5]
	v_mfma_f32_16x16x32_bf16 v[54:57], v[166:169], v[182:185], v[54:57]
	v_mfma_f32_16x16x32_bf16 v[50:53], v[174:177], v[182:185], v[50:53]
	v_mfma_f32_16x16x32_bf16 v[38:41], v[166:169], v[228:231], v[38:41]
	v_mfma_f32_16x16x32_bf16 v[34:37], v[174:177], v[228:231], v[34:37]
	v_mfma_f32_16x16x32_bf16 v[22:25], v[166:169], v[236:239], v[22:25]
	v_mfma_f32_16x16x32_bf16 v[18:21], v[174:177], v[236:239], v[18:21]
	v_mfma_f32_16x16x32_bf16 v[6:9], v[166:169], v[244:247], v[6:9]
	v_mfma_f32_16x16x32_bf16 v[2:5], v[174:177], v[244:247], v[2:5]
	s_barrier
	s_add_i32 s10, 0, 0x18000
	s_add_i32 s11, 0, 0x1c000
	v_add_u32_e32 v158, s10, v143
	v_add_u32_e32 v174, s11, v143
	ds_read_b128 v[146:149], v158
	ds_read_b128 v[150:153], v158 offset:1024
	ds_read_b128 v[154:157], v158 offset:2048
	ds_read_b128 v[158:161], v158 offset:3072
	ds_read_b128 v[162:165], v174
	ds_read_b128 v[166:169], v174 offset:1024
	ds_read_b128 v[170:173], v174 offset:2048
	ds_read_b128 v[174:177], v174 offset:3072
	s_add_u32 s8, s56, 0x40000
	s_addc_u32 s9, s57, 0
	s_mov_b32 m0, s60
	v_lshl_add_u64 v[248:249], s[8:9], 0, v[134:135]
	ds_read_b128 v[178:181], v145 offset:32768
	ds_read_b128 v[182:185], v145 offset:33792
	ds_read_b128 v[224:227], v145 offset:34816
	ds_read_b128 v[228:231], v145 offset:35840
	ds_read_b128 v[232:235], v145 offset:36864
	ds_read_b128 v[236:239], v145 offset:37888
	ds_read_b128 v[240:243], v145 offset:38912
	ds_read_b128 v[244:247], v145 offset:39936
	global_load_lds_dwordx4 v[248:249], off
	v_lshl_add_u64 v[248:249], s[8:9], 0, v[132:133]
	s_mov_b32 m0, s61
	s_nop 0
	global_load_lds_dwordx4 v[248:249], off
	s_waitcnt vmcnt(8)
	s_waitcnt lgkmcnt(0)
	s_barrier
	s_waitcnt lgkmcnt(0)
	v_mfma_f32_16x16x32_bf16 v[126:129], v[146:149], v[178:181], v[126:129]
	v_mfma_f32_16x16x32_bf16 v[122:125], v[154:157], v[178:181], v[122:125]
	v_mfma_f32_16x16x32_bf16 v[110:113], v[146:149], v[224:227], v[110:113]
	v_mfma_f32_16x16x32_bf16 v[106:109], v[154:157], v[224:227], v[106:109]
	v_mfma_f32_16x16x32_bf16 v[102:105], v[146:149], v[232:235], v[102:105]
	v_mfma_f32_16x16x32_bf16 v[98:101], v[154:157], v[232:235], v[98:101]
	v_mfma_f32_16x16x32_bf16 v[78:81], v[146:149], v[240:243], v[78:81]
	v_mfma_f32_16x16x32_bf16 v[74:77], v[154:157], v[240:243], v[74:77]
	v_mfma_f32_16x16x32_bf16 v[126:129], v[150:153], v[182:185], v[126:129]
	v_mfma_f32_16x16x32_bf16 v[122:125], v[158:161], v[182:185], v[122:125]
	v_mfma_f32_16x16x32_bf16 v[110:113], v[150:153], v[228:231], v[110:113]
	v_mfma_f32_16x16x32_bf16 v[106:109], v[158:161], v[228:231], v[106:109]
	v_mfma_f32_16x16x32_bf16 v[102:105], v[150:153], v[236:239], v[102:105]
	v_mfma_f32_16x16x32_bf16 v[98:101], v[158:161], v[236:239], v[98:101]
	v_mfma_f32_16x16x32_bf16 v[78:81], v[150:153], v[244:247], v[78:81]
	v_mfma_f32_16x16x32_bf16 v[74:77], v[158:161], v[244:247], v[74:77]
	v_mfma_f32_16x16x32_bf16 v[118:121], v[162:165], v[178:181], v[118:121]
	v_mfma_f32_16x16x32_bf16 v[114:117], v[170:173], v[178:181], v[114:117]
	v_mfma_f32_16x16x32_bf16 v[94:97], v[162:165], v[224:227], v[94:97]
	v_mfma_f32_16x16x32_bf16 v[90:93], v[170:173], v[224:227], v[90:93]
	v_mfma_f32_16x16x32_bf16 v[86:89], v[162:165], v[232:235], v[86:89]
	v_mfma_f32_16x16x32_bf16 v[82:85], v[170:173], v[232:235], v[82:85]
	v_mfma_f32_16x16x32_bf16 v[70:73], v[162:165], v[240:243], v[70:73]
	v_mfma_f32_16x16x32_bf16 v[66:69], v[170:173], v[240:243], v[66:69]
	v_mfma_f32_16x16x32_bf16 v[118:121], v[166:169], v[182:185], v[118:121]
	v_mfma_f32_16x16x32_bf16 v[114:117], v[174:177], v[182:185], v[114:117]
	v_mfma_f32_16x16x32_bf16 v[94:97], v[166:169], v[228:231], v[94:97]
	v_mfma_f32_16x16x32_bf16 v[90:93], v[174:177], v[228:231], v[90:93]
	v_mfma_f32_16x16x32_bf16 v[86:89], v[166:169], v[236:239], v[86:89]
	v_mfma_f32_16x16x32_bf16 v[82:85], v[174:177], v[236:239], v[82:85]
	v_mfma_f32_16x16x32_bf16 v[70:73], v[166:169], v[244:247], v[70:73]
	v_mfma_f32_16x16x32_bf16 v[66:69], v[174:177], v[244:247], v[66:69]
	s_barrier
	s_add_i32 s8, s10, s28
	v_lshl_add_u64 v[140:141], v[140:141], 0, s[26:27]
	s_mov_b32 m0, s8
	ds_read_b128 v[178:181], v145 offset:49152
	ds_read_b128 v[182:185], v145 offset:50176
	ds_read_b128 v[224:227], v145 offset:51200
	ds_read_b128 v[228:231], v145 offset:52224
	ds_read_b128 v[232:235], v145 offset:53248
	ds_read_b128 v[236:239], v145 offset:54272
	ds_read_b128 v[240:243], v145 offset:55296
	ds_read_b128 v[244:247], v145 offset:56320
	global_load_lds_dwordx4 v[140:141], off
	s_add_i32 m0, s8, 0x2000
	s_add_u32 s8, s54, 0x40080
	v_lshl_add_u64 v[140:141], v[186:187], 0, s[26:27]
	s_addc_u32 s9, s55, 0
	s_add_i32 s10, s11, s28
	global_load_lds_dwordx4 v[140:141], off
	v_lshl_add_u64 v[140:141], s[8:9], 0, v[0:1]
	s_mov_b32 m0, s10
	s_nop 0
	global_load_lds_dwordx4 v[140:141], off
	v_lshl_add_u64 v[140:141], s[8:9], 0, v[130:131]
	s_add_i32 m0, s10, 0x2000
	s_nop 0
	global_load_lds_dwordx4 v[140:141], off
	v_lshl_add_u64 v[140:141], v[202:203], 0, s[26:27]
	s_mov_b32 m0, s62
	s_nop 0
	global_load_lds_dwordx4 v[140:141], off
	v_lshl_add_u64 v[140:141], v[208:209], 0, s[26:27]
	s_mov_b32 m0, s63
	s_nop 0
	global_load_lds_dwordx4 v[140:141], off
	s_waitcnt vmcnt(8)
	s_waitcnt lgkmcnt(0)
	s_barrier
	s_waitcnt lgkmcnt(0)
	v_mfma_f32_16x16x32_bf16 v[62:65], v[146:149], v[178:181], v[62:65]
	v_mfma_f32_16x16x32_bf16 v[58:61], v[154:157], v[178:181], v[58:61]
	v_mfma_f32_16x16x32_bf16 v[46:49], v[146:149], v[224:227], v[46:49]
	v_mfma_f32_16x16x32_bf16 v[42:45], v[154:157], v[224:227], v[42:45]
	v_mfma_f32_16x16x32_bf16 v[30:33], v[146:149], v[232:235], v[30:33]
	v_mfma_f32_16x16x32_bf16 v[26:29], v[154:157], v[232:235], v[26:29]
	v_mfma_f32_16x16x32_bf16 v[14:17], v[146:149], v[240:243], v[14:17]
	v_mfma_f32_16x16x32_bf16 v[10:13], v[154:157], v[240:243], v[10:13]
	v_mfma_f32_16x16x32_bf16 v[62:65], v[150:153], v[182:185], v[62:65]
	v_mfma_f32_16x16x32_bf16 v[58:61], v[158:161], v[182:185], v[58:61]
	v_mfma_f32_16x16x32_bf16 v[46:49], v[150:153], v[228:231], v[46:49]
	v_mfma_f32_16x16x32_bf16 v[42:45], v[158:161], v[228:231], v[42:45]
	v_mfma_f32_16x16x32_bf16 v[30:33], v[150:153], v[236:239], v[30:33]
	v_mfma_f32_16x16x32_bf16 v[26:29], v[158:161], v[236:239], v[26:29]
	v_mfma_f32_16x16x32_bf16 v[14:17], v[150:153], v[244:247], v[14:17]
	v_mfma_f32_16x16x32_bf16 v[10:13], v[158:161], v[244:247], v[10:13]
	v_mfma_f32_16x16x32_bf16 v[54:57], v[162:165], v[178:181], v[54:57]
	v_mfma_f32_16x16x32_bf16 v[50:53], v[170:173], v[178:181], v[50:53]
	v_mfma_f32_16x16x32_bf16 v[38:41], v[162:165], v[224:227], v[38:41]
	v_mfma_f32_16x16x32_bf16 v[34:37], v[170:173], v[224:227], v[34:37]
	v_mfma_f32_16x16x32_bf16 v[22:25], v[162:165], v[232:235], v[22:25]
	v_mfma_f32_16x16x32_bf16 v[18:21], v[170:173], v[232:235], v[18:21]
	v_mfma_f32_16x16x32_bf16 v[6:9], v[162:165], v[240:243], v[6:9]
	v_mfma_f32_16x16x32_bf16 v[2:5], v[170:173], v[240:243], v[2:5]
	v_mfma_f32_16x16x32_bf16 v[54:57], v[166:169], v[182:185], v[54:57]
	v_mfma_f32_16x16x32_bf16 v[50:53], v[174:177], v[182:185], v[50:53]
	v_mfma_f32_16x16x32_bf16 v[38:41], v[166:169], v[228:231], v[38:41]
	v_mfma_f32_16x16x32_bf16 v[34:37], v[174:177], v[228:231], v[34:37]
	v_mfma_f32_16x16x32_bf16 v[22:25], v[166:169], v[236:239], v[22:25]
	v_mfma_f32_16x16x32_bf16 v[18:21], v[174:177], v[236:239], v[18:21]
	v_mfma_f32_16x16x32_bf16 v[6:9], v[166:169], v[244:247], v[6:9]
	v_mfma_f32_16x16x32_bf16 v[2:5], v[174:177], v[244:247], v[2:5]
	s_barrier
	s_add_i32 s73, s73, 2
	s_add_u32 s52, s52, 0x100
	s_addc_u32 s53, s53, 0
	s_add_u32 s69, s69, 0x100
	s_addc_u32 s72, s72, 0
	s_cmp_gt_u32 s73, 13
	s_cbranch_scc0 .LBB0_1538
	s_and_b64 vcc, exec, s[42:43]
	s_mov_b64 s[68:69], s[36:37]
	s_cbranch_vccz .LBB0_1541
	s_barrier

.LBB0_1549:
	s_add_i32 s10, s44, 0x100
	s_and_b64 s[8:9], s[42:43], exec
	s_cselect_b32 s9, 0, s10
	s_cselect_b32 s8, 0, 0
	s_add_u32 s46, s72, s9
	s_addc_u32 s47, s73, s8
	s_add_i32 s10, 0, 0x10000
	s_add_u32 s48, s38, s9
	s_addc_u32 s49, s39, s8
	s_add_i32 s8, 0, 0x14000
	s_add_u32 s52, s68, s44
	s_addc_u32 s53, s69, 0
	s_add_i32 s67, s10, s54
	s_add_i32 m0, s4, 0xc000
	s_add_i32 s9, s4, 0xe000
	s_add_i32 s64, s67, 0x2000
	s_add_u32 s50, s48, 0x40000
	s_addc_u32 s51, s49, 0
	s_add_i32 s66, s8, s54
	v_add_u32_e32 v148, s10, v134
	v_add_u32_e32 v164, s8, v134
	s_add_i32 s65, s66, 0x2000
	s_add_i32 s63, 0, 0x18000
	s_add_i32 s62, 0, 0x1c000
	ds_read_b128 v[136:139], v148
	ds_read_b128 v[140:143], v148 offset:1024
	ds_read_b128 v[144:147], v148 offset:2048
	ds_read_b128 v[148:151], v148 offset:3072
	ds_read_b128 v[152:155], v164
	ds_read_b128 v[156:159], v164 offset:1024
	ds_read_b128 v[160:163], v164 offset:2048
	ds_read_b128 v[164:167], v164 offset:3072
	s_add_u32 s44, s46, 0x40000
	s_addc_u32 s45, s47, 0
	s_add_i32 s61, s63, s54
	s_add_i32 s60, s61, 0x2000
	s_add_u32 s42, s48, 0x40080
	s_addc_u32 s43, s49, 0
	s_add_i32 s69, s62, s54
	s_add_i32 s68, s69, 0x2000
	v_lshl_add_u64 v[202:203], s[52:53], 0, v[0:1]
	v_lshl_add_u64 v[202:203], v[202:203], 0, s[26:27]
	ds_read_b128 v[168:171], v135
	ds_read_b128 v[172:175], v135 offset:1024
	ds_read_b128 v[176:179], v135 offset:2048
	ds_read_b128 v[180:183], v135 offset:3072
	ds_read_b128 v[184:187], v135 offset:4096
	ds_read_b128 v[224:227], v135 offset:5120
	ds_read_b128 v[228:231], v135 offset:6144
	ds_read_b128 v[232:235], v135 offset:7168
	global_load_lds_dwordx4 v[202:203], off
	v_lshl_add_u64 v[202:203], s[52:53], 0, v[130:131]
	v_lshl_add_u64 v[202:203], v[202:203], 0, s[26:27]
	s_mov_b32 m0, s9
	s_nop 0
	global_load_lds_dwordx4 v[202:203], off
	s_waitcnt vmcnt(8)
	s_waitcnt lgkmcnt(0)
	s_barrier
	s_waitcnt lgkmcnt(0)
	v_mfma_f32_16x16x32_bf16 v[126:129], v[136:139], v[168:171], v[126:129]
	v_mfma_f32_16x16x32_bf16 v[122:125], v[144:147], v[168:171], v[122:125]
	v_mfma_f32_16x16x32_bf16 v[118:121], v[136:139], v[176:179], v[118:121]
	v_mfma_f32_16x16x32_bf16 v[114:117], v[144:147], v[176:179], v[114:117]
	v_mfma_f32_16x16x32_bf16 v[102:105], v[136:139], v[184:187], v[102:105]
	v_mfma_f32_16x16x32_bf16 v[98:101], v[144:147], v[184:187], v[98:101]
	v_mfma_f32_16x16x32_bf16 v[86:89], v[136:139], v[228:231], v[86:89]
	v_mfma_f32_16x16x32_bf16 v[82:85], v[144:147], v[228:231], v[82:85]
	v_mfma_f32_16x16x32_bf16 v[126:129], v[140:143], v[172:175], v[126:129]
	v_mfma_f32_16x16x32_bf16 v[122:125], v[148:151], v[172:175], v[122:125]
	v_mfma_f32_16x16x32_bf16 v[118:121], v[140:143], v[180:183], v[118:121]
	v_mfma_f32_16x16x32_bf16 v[114:117], v[148:151], v[180:183], v[114:117]
	v_mfma_f32_16x16x32_bf16 v[102:105], v[140:143], v[224:227], v[102:105]
	v_mfma_f32_16x16x32_bf16 v[98:101], v[148:151], v[224:227], v[98:101]
	v_mfma_f32_16x16x32_bf16 v[86:89], v[140:143], v[232:235], v[86:89]
	v_mfma_f32_16x16x32_bf16 v[82:85], v[148:151], v[232:235], v[82:85]
	v_mfma_f32_16x16x32_bf16 v[110:113], v[152:155], v[168:171], v[110:113]
	v_mfma_f32_16x16x32_bf16 v[106:109], v[160:163], v[168:171], v[106:109]
	v_mfma_f32_16x16x32_bf16 v[94:97], v[152:155], v[176:179], v[94:97]
	v_mfma_f32_16x16x32_bf16 v[90:93], v[160:163], v[176:179], v[90:93]
	v_mfma_f32_16x16x32_bf16 v[78:81], v[152:155], v[184:187], v[78:81]
	v_mfma_f32_16x16x32_bf16 v[74:77], v[160:163], v[184:187], v[74:77]
	v_mfma_f32_16x16x32_bf16 v[70:73], v[152:155], v[228:231], v[70:73]
	v_mfma_f32_16x16x32_bf16 v[66:69], v[160:163], v[228:231], v[66:69]
	v_mfma_f32_16x16x32_bf16 v[110:113], v[156:159], v[172:175], v[110:113]
	v_mfma_f32_16x16x32_bf16 v[106:109], v[164:167], v[172:175], v[106:109]
	v_mfma_f32_16x16x32_bf16 v[94:97], v[156:159], v[180:183], v[94:97]
	v_mfma_f32_16x16x32_bf16 v[90:93], v[164:167], v[180:183], v[90:93]
	v_mfma_f32_16x16x32_bf16 v[78:81], v[156:159], v[224:227], v[78:81]
	v_mfma_f32_16x16x32_bf16 v[74:77], v[164:167], v[224:227], v[74:77]
	v_mfma_f32_16x16x32_bf16 v[70:73], v[156:159], v[232:235], v[70:73]
	v_mfma_f32_16x16x32_bf16 v[66:69], v[164:167], v[232:235], v[66:69]
	s_barrier
	s_mov_b32 m0, s67
	v_lshl_add_u64 v[202:203], s[48:49], 0, v[0:1]
	ds_read_b128 v[168:171], v135 offset:16384
	ds_read_b128 v[172:175], v135 offset:17408
	ds_read_b128 v[176:179], v135 offset:18432
	ds_read_b128 v[180:183], v135 offset:19456
	ds_read_b128 v[184:187], v135 offset:20480
	ds_read_b128 v[224:227], v135 offset:21504
	ds_read_b128 v[228:231], v135 offset:22528
	ds_read_b128 v[232:235], v135 offset:23552
	global_load_lds_dwordx4 v[202:203], off
	v_lshl_add_u64 v[208:209], s[48:49], 0, v[130:131]
	s_mov_b32 m0, s64
	v_lshl_add_u64 v[236:237], s[50:51], 0, v[0:1]
	global_load_lds_dwordx4 v[208:209], off
	s_mov_b32 m0, s66
	v_lshl_add_u64 v[238:239], s[46:47], 0, v[130:131]
	global_load_lds_dwordx4 v[236:237], off
	v_lshl_add_u64 v[236:237], s[50:51], 0, v[130:131]
	s_mov_b32 m0, s65
	s_nop 0
	global_load_lds_dwordx4 v[236:237], off
	v_lshl_add_u64 v[236:237], s[46:47], 0, v[0:1]
	s_mov_b32 m0, s4
	s_nop 0
	global_load_lds_dwordx4 v[236:237], off
	s_mov_b32 m0, s5
	s_nop 0
	global_load_lds_dwordx4 v[238:239], off
	s_waitcnt vmcnt(8)
	s_waitcnt lgkmcnt(0)
	s_barrier
	s_waitcnt lgkmcnt(0)
	v_mfma_f32_16x16x32_bf16 v[62:65], v[136:139], v[168:171], v[62:65]
	v_mfma_f32_16x16x32_bf16 v[58:61], v[144:147], v[168:171], v[58:61]
	v_mfma_f32_16x16x32_bf16 v[54:57], v[136:139], v[176:179], v[54:57]
	v_mfma_f32_16x16x32_bf16 v[50:53], v[144:147], v[176:179], v[50:53]
	v_mfma_f32_16x16x32_bf16 v[38:41], v[136:139], v[184:187], v[38:41]
	v_mfma_f32_16x16x32_bf16 v[34:37], v[144:147], v[184:187], v[34:37]
	v_mfma_f32_16x16x32_bf16 v[22:25], v[136:139], v[228:231], v[22:25]
	v_mfma_f32_16x16x32_bf16 v[18:21], v[144:147], v[228:231], v[18:21]
	v_mfma_f32_16x16x32_bf16 v[62:65], v[140:143], v[172:175], v[62:65]
	v_mfma_f32_16x16x32_bf16 v[58:61], v[148:151], v[172:175], v[58:61]
	v_mfma_f32_16x16x32_bf16 v[54:57], v[140:143], v[180:183], v[54:57]
	v_mfma_f32_16x16x32_bf16 v[50:53], v[148:151], v[180:183], v[50:53]
	v_mfma_f32_16x16x32_bf16 v[38:41], v[140:143], v[224:227], v[38:41]
	v_mfma_f32_16x16x32_bf16 v[34:37], v[148:151], v[224:227], v[34:37]
	v_mfma_f32_16x16x32_bf16 v[22:25], v[140:143], v[232:235], v[22:25]
	v_mfma_f32_16x16x32_bf16 v[18:21], v[148:151], v[232:235], v[18:21]
	v_mfma_f32_16x16x32_bf16 v[46:49], v[152:155], v[168:171], v[46:49]
	v_mfma_f32_16x16x32_bf16 v[42:45], v[160:163], v[168:171], v[42:45]
	v_mfma_f32_16x16x32_bf16 v[30:33], v[152:155], v[176:179], v[30:33]
	v_mfma_f32_16x16x32_bf16 v[26:29], v[160:163], v[176:179], v[26:29]
	v_mfma_f32_16x16x32_bf16 v[14:17], v[152:155], v[184:187], v[14:17]
	v_mfma_f32_16x16x32_bf16 v[10:13], v[160:163], v[184:187], v[10:13]
	v_mfma_f32_16x16x32_bf16 v[6:9], v[152:155], v[228:231], v[6:9]
	v_mfma_f32_16x16x32_bf16 v[2:5], v[160:163], v[228:231], v[2:5]
	v_mfma_f32_16x16x32_bf16 v[46:49], v[156:159], v[172:175], v[46:49]
	v_mfma_f32_16x16x32_bf16 v[42:45], v[164:167], v[172:175], v[42:45]
	v_mfma_f32_16x16x32_bf16 v[30:33], v[156:159], v[180:183], v[30:33]
	v_mfma_f32_16x16x32_bf16 v[26:29], v[164:167], v[180:183], v[26:29]
	v_mfma_f32_16x16x32_bf16 v[14:17], v[156:159], v[224:227], v[14:17]
	v_mfma_f32_16x16x32_bf16 v[10:13], v[164:167], v[224:227], v[10:13]
	v_mfma_f32_16x16x32_bf16 v[6:9], v[156:159], v[232:235], v[6:9]
	v_mfma_f32_16x16x32_bf16 v[2:5], v[164:167], v[232:235], v[2:5]
	s_barrier
	v_add_u32_e32 v148, s63, v134
	v_add_u32_e32 v164, s62, v134
	ds_read_b128 v[136:139], v148
	ds_read_b128 v[140:143], v148 offset:1024
	ds_read_b128 v[144:147], v148 offset:2048
	ds_read_b128 v[148:151], v148 offset:3072
	ds_read_b128 v[152:155], v164
	ds_read_b128 v[156:159], v164 offset:1024
	ds_read_b128 v[160:163], v164 offset:2048
	ds_read_b128 v[164:167], v164 offset:3072
	s_mov_b32 m0, s55
	v_lshl_add_u64 v[240:241], s[44:45], 0, v[0:1]
	ds_read_b128 v[168:171], v135 offset:32768
	ds_read_b128 v[172:175], v135 offset:33792
	ds_read_b128 v[176:179], v135 offset:34816
	ds_read_b128 v[180:183], v135 offset:35840
	ds_read_b128 v[184:187], v135 offset:36864
	ds_read_b128 v[224:227], v135 offset:37888
	ds_read_b128 v[228:231], v135 offset:38912
	ds_read_b128 v[232:235], v135 offset:39936
	global_load_lds_dwordx4 v[240:241], off
	v_lshl_add_u64 v[240:241], s[44:45], 0, v[130:131]
	s_mov_b32 m0, s56
	s_nop 0
	global_load_lds_dwordx4 v[240:241], off
	s_waitcnt vmcnt(8)
	s_waitcnt lgkmcnt(0)
	s_barrier
	s_waitcnt lgkmcnt(0)
	v_mfma_f32_16x16x32_bf16 v[126:129], v[136:139], v[168:171], v[126:129]
	v_mfma_f32_16x16x32_bf16 v[122:125], v[144:147], v[168:171], v[122:125]
	v_mfma_f32_16x16x32_bf16 v[118:121], v[136:139], v[176:179], v[118:121]
	v_mfma_f32_16x16x32_bf16 v[114:117], v[144:147], v[176:179], v[114:117]
	v_mfma_f32_16x16x32_bf16 v[102:105], v[136:139], v[184:187], v[102:105]
	v_mfma_f32_16x16x32_bf16 v[98:101], v[144:147], v[184:187], v[98:101]
	v_mfma_f32_16x16x32_bf16 v[86:89], v[136:139], v[228:231], v[86:89]
	v_mfma_f32_16x16x32_bf16 v[82:85], v[144:147], v[228:231], v[82:85]
	v_mfma_f32_16x16x32_bf16 v[126:129], v[140:143], v[172:175], v[126:129]
	v_mfma_f32_16x16x32_bf16 v[122:125], v[148:151], v[172:175], v[122:125]
	v_mfma_f32_16x16x32_bf16 v[118:121], v[140:143], v[180:183], v[118:121]
	v_mfma_f32_16x16x32_bf16 v[114:117], v[148:151], v[180:183], v[114:117]
	v_mfma_f32_16x16x32_bf16 v[102:105], v[140:143], v[224:227], v[102:105]
	v_mfma_f32_16x16x32_bf16 v[98:101], v[148:151], v[224:227], v[98:101]
	v_mfma_f32_16x16x32_bf16 v[86:89], v[140:143], v[232:235], v[86:89]
	v_mfma_f32_16x16x32_bf16 v[82:85], v[148:151], v[232:235], v[82:85]
	v_mfma_f32_16x16x32_bf16 v[110:113], v[152:155], v[168:171], v[110:113]
	v_mfma_f32_16x16x32_bf16 v[106:109], v[160:163], v[168:171], v[106:109]
	v_mfma_f32_16x16x32_bf16 v[94:97], v[152:155], v[176:179], v[94:97]
	v_mfma_f32_16x16x32_bf16 v[90:93], v[160:163], v[176:179], v[90:93]
	v_mfma_f32_16x16x32_bf16 v[78:81], v[152:155], v[184:187], v[78:81]
	v_mfma_f32_16x16x32_bf16 v[74:77], v[160:163], v[184:187], v[74:77]
	v_mfma_f32_16x16x32_bf16 v[70:73], v[152:155], v[228:231], v[70:73]
	v_mfma_f32_16x16x32_bf16 v[66:69], v[160:163], v[228:231], v[66:69]
	v_mfma_f32_16x16x32_bf16 v[110:113], v[156:159], v[172:175], v[110:113]
	v_mfma_f32_16x16x32_bf16 v[106:109], v[164:167], v[172:175], v[106:109]
	v_mfma_f32_16x16x32_bf16 v[94:97], v[156:159], v[180:183], v[94:97]
	v_mfma_f32_16x16x32_bf16 v[90:93], v[164:167], v[180:183], v[90:93]
	v_mfma_f32_16x16x32_bf16 v[78:81], v[156:159], v[224:227], v[78:81]
	v_mfma_f32_16x16x32_bf16 v[74:77], v[164:167], v[224:227], v[74:77]
	v_mfma_f32_16x16x32_bf16 v[70:73], v[156:159], v[232:235], v[70:73]
	v_mfma_f32_16x16x32_bf16 v[66:69], v[164:167], v[232:235], v[66:69]
	s_barrier
	s_mov_b32 m0, s61
	v_lshl_add_u64 v[202:203], v[202:203], 0, s[26:27]
	ds_read_b128 v[168:171], v135 offset:49152
	ds_read_b128 v[172:175], v135 offset:50176
	ds_read_b128 v[176:179], v135 offset:51200
	ds_read_b128 v[180:183], v135 offset:52224
	ds_read_b128 v[184:187], v135 offset:53248
	ds_read_b128 v[224:227], v135 offset:54272
	ds_read_b128 v[228:231], v135 offset:55296
	ds_read_b128 v[232:235], v135 offset:56320
	global_load_lds_dwordx4 v[202:203], off
	v_lshl_add_u64 v[202:203], v[208:209], 0, s[26:27]
	s_mov_b32 m0, s60
	s_nop 0
	global_load_lds_dwordx4 v[202:203], off
	v_lshl_add_u64 v[202:203], s[42:43], 0, v[0:1]
	s_mov_b32 m0, s69
	s_nop 0
	global_load_lds_dwordx4 v[202:203], off
	v_lshl_add_u64 v[202:203], s[42:43], 0, v[130:131]
	s_mov_b32 m0, s68
	s_mov_b64 s[68:69], s[36:37]
	global_load_lds_dwordx4 v[202:203], off
	v_lshl_add_u64 v[202:203], v[236:237], 0, s[26:27]
	s_mov_b32 m0, s58
	s_nop 0
	global_load_lds_dwordx4 v[202:203], off
	v_lshl_add_u64 v[202:203], v[238:239], 0, s[26:27]
	s_mov_b32 m0, s59
	s_nop 0
	global_load_lds_dwordx4 v[202:203], off
	s_waitcnt vmcnt(8)
	s_waitcnt lgkmcnt(0)
	s_barrier
	s_waitcnt lgkmcnt(0)
	v_mfma_f32_16x16x32_bf16 v[62:65], v[136:139], v[168:171], v[62:65]
	v_mfma_f32_16x16x32_bf16 v[58:61], v[144:147], v[168:171], v[58:61]
	v_mfma_f32_16x16x32_bf16 v[54:57], v[136:139], v[176:179], v[54:57]
	v_mfma_f32_16x16x32_bf16 v[50:53], v[144:147], v[176:179], v[50:53]
	v_mfma_f32_16x16x32_bf16 v[38:41], v[136:139], v[184:187], v[38:41]
	v_mfma_f32_16x16x32_bf16 v[34:37], v[144:147], v[184:187], v[34:37]
	v_mfma_f32_16x16x32_bf16 v[22:25], v[136:139], v[228:231], v[22:25]
	v_mfma_f32_16x16x32_bf16 v[18:21], v[144:147], v[228:231], v[18:21]
	v_mfma_f32_16x16x32_bf16 v[62:65], v[140:143], v[172:175], v[62:65]
	v_mfma_f32_16x16x32_bf16 v[58:61], v[148:151], v[172:175], v[58:61]
	v_mfma_f32_16x16x32_bf16 v[54:57], v[140:143], v[180:183], v[54:57]
	v_mfma_f32_16x16x32_bf16 v[50:53], v[148:151], v[180:183], v[50:53]
	v_mfma_f32_16x16x32_bf16 v[38:41], v[140:143], v[224:227], v[38:41]
	v_mfma_f32_16x16x32_bf16 v[34:37], v[148:151], v[224:227], v[34:37]
	v_mfma_f32_16x16x32_bf16 v[22:25], v[140:143], v[232:235], v[22:25]
	v_mfma_f32_16x16x32_bf16 v[18:21], v[148:151], v[232:235], v[18:21]
	v_mfma_f32_16x16x32_bf16 v[46:49], v[152:155], v[168:171], v[46:49]
	v_mfma_f32_16x16x32_bf16 v[42:45], v[160:163], v[168:171], v[42:45]
	v_mfma_f32_16x16x32_bf16 v[30:33], v[152:155], v[176:179], v[30:33]
	v_mfma_f32_16x16x32_bf16 v[26:29], v[160:163], v[176:179], v[26:29]
	v_mfma_f32_16x16x32_bf16 v[14:17], v[152:155], v[184:187], v[14:17]
	v_mfma_f32_16x16x32_bf16 v[10:13], v[160:163], v[184:187], v[10:13]
	v_mfma_f32_16x16x32_bf16 v[6:9], v[152:155], v[228:231], v[6:9]
	v_mfma_f32_16x16x32_bf16 v[2:5], v[160:163], v[228:231], v[2:5]
	v_mfma_f32_16x16x32_bf16 v[46:49], v[156:159], v[172:175], v[46:49]
	v_mfma_f32_16x16x32_bf16 v[42:45], v[164:167], v[172:175], v[42:45]
	v_mfma_f32_16x16x32_bf16 v[30:33], v[156:159], v[180:183], v[30:33]
	v_mfma_f32_16x16x32_bf16 v[26:29], v[164:167], v[180:183], v[26:29]
	v_mfma_f32_16x16x32_bf16 v[14:17], v[156:159], v[224:227], v[14:17]
	v_mfma_f32_16x16x32_bf16 v[10:13], v[164:167], v[224:227], v[10:13]
	v_mfma_f32_16x16x32_bf16 v[6:9], v[156:159], v[232:235], v[6:9]
	v_mfma_f32_16x16x32_bf16 v[2:5], v[164:167], v[232:235], v[2:5]
	s_barrier
	s_andn2_b64 vcc, exec, s[40:41]
	s_mov_b64 s[42:43], -1
	s_mov_b64 s[40:41], 0
	s_movk_i32 s44, 0x100
	s_cbranch_vccz .LBB0_1549
	v_readlane_b32 s4, v254, 17
	s_lshr_b32 s5, s2, 4
	v_and_b32_e32 v0, 63, v204
	v_lshrrev_b32_e32 v130, 5, v0
	v_and_b32_e32 v131, 31, v0
	s_lshr_b32 vcc_lo, s28, 8
	s_lshl_b32 vcc_lo, vcc_lo, 6
	v_add_u32_e32 v134, vcc_lo, v130
	v_lshlrev_b32_e32 v134, 12, v134
	s_or_b32 vcc_hi, s4, s57
	v_or_b32_e32 v135, vcc_hi, v131
	v_lshl_add_u32 v134, v135, 2, v134
	v_add_u32_e32 v134, 0x8000000, v134
	s_lshr_b32 vcc_lo, s28, 6
	s_mul_i32 vcc_lo, vcc_lo, 0x900
	s_add_u32 vcc_lo, vcc_lo, 0x20200
	v_and_b32_e32 v136, 15, v132
	v_mul_u32_u24_e32 v136, 0x90, v136
	v_lshl_add_u32 v136, v133, 4, v136
	v_add_u32_e32 v136, vcc_lo, v136
	v_mul_u32_u24_e32 v137, 0x90, v130
	v_lshl_add_u32 v137, v131, 2, v137
	v_add_u32_e32 v137, vcc_lo, v137
	s_cmp_lg_u32 s5, 0
	s_cbranch_scc1 .Lg4s_q1
	v_mov_b32_e32 v138, v134
	v_add_u32_e32 v139, 0x2000, v134
	v_add_u32_e32 v140, 0x4000, v134
	v_add_u32_e32 v141, 0x6000, v134
	v_add_u32_e32 v142, 0x8000, v134
	v_add_u32_e32 v143, 0xa000, v134
	v_add_u32_e32 v144, 0xc000, v134
	v_add_u32_e32 v145, 0xe000, v134
	ds_write_b128 v136, v[126:129]
	ds_write_b128 v136, v[122:125] offset:64
	ds_read_b32 v146, v137
	ds_read_b32 v147, v137 offset:288
	ds_read_b32 v148, v137 offset:576
	ds_read_b32 v149, v137 offset:864
	ds_read_b32 v150, v137 offset:1152
	ds_read_b32 v151, v137 offset:1440
	ds_read_b32 v152, v137 offset:1728
	ds_read_b32 v153, v137 offset:2016
	s_waitcnt lgkmcnt(0)
	global_atomic_add_f32 v138, v146, s[24:25]
	global_atomic_add_f32 v139, v147, s[24:25]
	global_atomic_add_f32 v140, v148, s[24:25]
	global_atomic_add_f32 v141, v149, s[24:25]
	global_atomic_add_f32 v142, v150, s[24:25]
	global_atomic_add_f32 v143, v151, s[24:25]
	global_atomic_add_f32 v144, v152, s[24:25]
	global_atomic_add_f32 v145, v153, s[24:25]
	ds_write_b128 v136, v[110:113]
	ds_write_b128 v136, v[106:109] offset:64
	ds_read_b32 v154, v137
	ds_read_b32 v155, v137 offset:288
	ds_read_b32 v156, v137 offset:576
	ds_read_b32 v157, v137 offset:864
	ds_read_b32 v158, v137 offset:1152
	ds_read_b32 v159, v137 offset:1440
	ds_read_b32 v160, v137 offset:1728
	ds_read_b32 v161, v137 offset:2016
	s_waitcnt lgkmcnt(0)
	global_atomic_add_f32 v138, v154, s[24:25] offset:512
	global_atomic_add_f32 v139, v155, s[24:25] offset:512
	global_atomic_add_f32 v140, v156, s[24:25] offset:512
	global_atomic_add_f32 v141, v157, s[24:25] offset:512
	global_atomic_add_f32 v142, v158, s[24:25] offset:512
	global_atomic_add_f32 v143, v159, s[24:25] offset:512
	global_atomic_add_f32 v144, v160, s[24:25] offset:512
	global_atomic_add_f32 v145, v161, s[24:25] offset:512
